# phase-0 adaLN GEMV loop: early vmcnt waits moved behind the issue of all 32 row loads (counted waits); LoRA-2 a-epilogue bias loaded once
# speedup vs baseline: 1.0032x; 1.0002x over previous
.LBB0_52:
	v_add_co_u32_e32 v46, vcc, s1, v40
	global_load_dwordx4 v[26:29], v[40:41], off nt
	s_nop 0
	v_addc_co_u32_e32 v47, vcc, 0, v41, vcc
	v_add_co_u32_e32 v42, vcc, s3, v40
	global_load_dwordx4 v[18:21], v[38:39], off offset:48
	global_load_dwordx4 v[22:25], v[38:39], off offset:32
	global_load_dwordx4 v[30:33], v[38:39], off offset:16
	global_load_dwordx4 v[34:37], v[38:39], off
	v_addc_co_u32_e32 v43, vcc, 0, v41, vcc
	v_add_co_u32_e32 v44, vcc, s26, v40
	v_lshl_add_u64 v[72:73], v[38:39], 0, s[12:13]
	s_nop 0
	v_addc_co_u32_e32 v45, vcc, 0, v41, vcc
	v_add_co_u32_e32 v48, vcc, s27, v40
	v_lshl_add_u64 v[120:121], v[38:39], 0, s[14:15]
	s_nop 0
	v_addc_co_u32_e32 v49, vcc, 0, v41, vcc
	v_add_co_u32_e32 v50, vcc, s28, v40
	v_lshl_add_u64 v[124:125], v[38:39], 0, s[20:21]
	s_nop 0
	v_addc_co_u32_e32 v51, vcc, 0, v41, vcc
	v_add_co_u32_e32 v52, vcc, s29, v40
	s_add_i32 s24, s24, 16
	s_nop 0
	v_addc_co_u32_e32 v53, vcc, 0, v41, vcc
	v_add_co_u32_e32 v54, vcc, s30, v40
	s_cmpk_gt_u32 s24, 0x6f
	s_nop 0
	v_addc_co_u32_e32 v55, vcc, 0, v41, vcc
	v_add_co_u32_e32 v56, vcc, s31, v40
	s_nop 0
	s_nop 0
	v_addc_co_u32_e32 v57, vcc, 0, v41, vcc
	v_add_co_u32_e32 v58, vcc, s33, v40
	s_nop 0
	s_nop 0
	v_addc_co_u32_e32 v59, vcc, 0, v41, vcc
	v_add_co_u32_e32 v60, vcc, s34, v40
	s_nop 0
	s_nop 0
	v_addc_co_u32_e32 v61, vcc, 0, v41, vcc
	v_add_co_u32_e32 v62, vcc, s35, v40
	s_nop 0
	s_nop 0
	v_addc_co_u32_e32 v63, vcc, 0, v41, vcc
	v_add_co_u32_e32 v64, vcc, s36, v40
	s_nop 0
	s_nop 0
	v_addc_co_u32_e32 v65, vcc, 0, v41, vcc
	v_add_co_u32_e32 v66, vcc, s37, v40
	s_nop 1
	v_addc_co_u32_e32 v67, vcc, 0, v41, vcc
	v_add_co_u32_e32 v68, vcc, s38, v40
	s_nop 1
	v_addc_co_u32_e32 v69, vcc, 0, v41, vcc
	v_add_co_u32_e32 v70, vcc, s39, v40
	s_nop 1
	v_addc_co_u32_e32 v71, vcc, 0, v41, vcc
	v_add_co_u32_e32 v74, vcc, s40, v38
	v_lshl_add_u64 v[40:41], v[40:41], 0, s[22:23]
	s_nop 0
	v_addc_co_u32_e32 v75, vcc, 0, v39, vcc
	v_add_co_u32_e32 v84, vcc, s41, v38
	s_nop 1
	v_addc_co_u32_e32 v85, vcc, 0, v39, vcc
	v_add_co_u32_e32 v88, vcc, s43, v38
	s_nop 1
	v_addc_co_u32_e32 v89, vcc, 0, v39, vcc
	global_load_dwordx4 v[80:83], v[74:75], off
	s_nop 0
	global_load_dwordx4 v[84:87], v[84:85], off
	s_nop 0
	global_load_dwordx4 v[88:91], v[88:89], off
	s_nop 0
	global_load_dwordx4 v[92:95], v[46:47], off nt
	global_load_dwordx4 v[96:99], v[72:73], off offset:16
	global_load_dwordx4 v[100:103], v[120:121], off offset:16
	global_load_dwordx4 v[104:107], v[124:125], off offset:16
	global_load_dwordx4 v[108:111], v[72:73], off offset:32
	global_load_dwordx4 v[112:115], v[120:121], off offset:32
	global_load_dwordx4 v[116:119], v[124:125], off offset:32
	s_nop 0
	global_load_dwordx4 v[72:75], v[72:73], off offset:48
	s_nop 0
	global_load_dwordx4 v[120:123], v[120:121], off offset:48
	s_nop 0
	global_load_dwordx4 v[124:127], v[124:125], off offset:48
	s_nop 0
	global_load_dwordx4 v[128:131], v[42:43], off nt
	s_nop 0
	global_load_dwordx4 v[42:45], v[44:45], off nt
	s_nop 0
	global_load_dwordx4 v[46:49], v[48:49], off nt
	s_nop 0
	global_load_dwordx4 v[132:135], v[50:51], off nt
	s_nop 0
	global_load_dwordx4 v[50:53], v[52:53], off nt
	s_nop 0
	global_load_dwordx4 v[136:139], v[54:55], off nt
	s_nop 0
	global_load_dwordx4 v[54:57], v[56:57], off nt
	s_nop 0
	global_load_dwordx4 v[140:143], v[58:59], off nt
	s_nop 0
	global_load_dwordx4 v[58:61], v[60:61], off nt
	s_nop 0
	global_load_dwordx4 v[144:147], v[62:63], off nt
	s_nop 0
	global_load_dwordx4 v[62:65], v[64:65], off nt
	s_nop 0
	global_load_dwordx4 v[148:151], v[66:67], off nt
	s_nop 0
	global_load_dwordx4 v[66:69], v[68:69], off nt
	s_nop 0
	global_load_dwordx4 v[152:155], v[70:71], off nt
	s_waitcnt vmcnt(30)
	v_mov_b32_e32 v160, v21
	s_waitcnt vmcnt(27)
	v_pk_fma_f32 v[16:17], v[28:29], v[34:35], v[16:17] op_sel_hi:[1,0,1]
	v_pk_fma_f32 v[14:15], v[26:27], v[34:35], v[14:15] op_sel_hi:[1,0,1]
	v_mov_b32_e32 v156, v33
	v_mov_b32_e32 v158, v25
	v_mov_b32_e32 v70, v37
	v_lshl_add_u64 v[38:39], v[38:39], 0, 64
	s_waitcnt vmcnt(26)
	v_pk_fma_f32 v[12:13], v[28:29], v[80:81], v[12:13] op_sel_hi:[1,0,1]
	v_pk_fma_f32 v[10:11], v[26:27], v[80:81], v[10:11] op_sel_hi:[1,0,1]
	s_waitcnt vmcnt(25)
	v_pk_fma_f32 v[8:9], v[28:29], v[84:85], v[8:9] op_sel_hi:[1,0,1]
	v_pk_fma_f32 v[6:7], v[26:27], v[84:85], v[6:7] op_sel_hi:[1,0,1]
	s_waitcnt vmcnt(24)
	v_pk_fma_f32 v[4:5], v[28:29], v[88:89], v[4:5] op_sel_hi:[1,0,1]
	v_pk_fma_f32 v[2:3], v[26:27], v[88:89], v[2:3] op_sel_hi:[1,0,1]
	s_waitcnt vmcnt(23)
	v_pk_fma_f32 v[16:17], v[94:95], v[34:35], v[16:17] op_sel:[0,1,0]
	v_pk_fma_f32 v[14:15], v[92:93], v[34:35], v[14:15] op_sel:[0,1,0]
	v_pk_fma_f32 v[10:11], v[92:93], v[80:81], v[10:11] op_sel:[0,1,0]
	v_pk_fma_f32 v[12:13], v[94:95], v[80:81], v[12:13] op_sel:[0,1,0]
	v_pk_fma_f32 v[6:7], v[92:93], v[84:85], v[6:7] op_sel:[0,1,0]
	v_pk_fma_f32 v[8:9], v[94:95], v[84:85], v[8:9] op_sel:[0,1,0]
	v_pk_fma_f32 v[2:3], v[92:93], v[88:89], v[2:3] op_sel:[0,1,0]
	v_pk_fma_f32 v[4:5], v[94:95], v[88:89], v[4:5] op_sel:[0,1,0]
	v_mov_b32_e32 v26, v83
	v_mov_b32_e32 v28, v87
	v_mov_b32_e32 v34, v91
	s_waitcnt vmcnt(13)
	v_pk_fma_f32 v[16:17], v[130:131], v[36:37], v[16:17] op_sel_hi:[1,0,1]
	v_pk_fma_f32 v[14:15], v[128:129], v[36:37], v[14:15] op_sel_hi:[1,0,1]
	v_pk_fma_f32 v[10:11], v[128:129], v[82:83], v[10:11] op_sel_hi:[1,0,1]
	v_pk_fma_f32 v[12:13], v[130:131], v[82:83], v[12:13] op_sel_hi:[1,0,1]
	v_pk_fma_f32 v[6:7], v[128:129], v[86:87], v[6:7] op_sel_hi:[1,0,1]
	v_pk_fma_f32 v[8:9], v[130:131], v[86:87], v[8:9] op_sel_hi:[1,0,1]
	v_pk_fma_f32 v[2:3], v[128:129], v[90:91], v[2:3] op_sel_hi:[1,0,1]
	v_pk_fma_f32 v[4:5], v[130:131], v[90:91], v[4:5] op_sel_hi:[1,0,1]
	s_waitcnt vmcnt(12)
	v_pk_fma_f32 v[16:17], v[44:45], v[70:71], v[16:17] op_sel_hi:[1,0,1]
	v_pk_fma_f32 v[14:15], v[42:43], v[70:71], v[14:15] op_sel_hi:[1,0,1]
	v_pk_fma_f32 v[12:13], v[44:45], v[26:27], v[12:13] op_sel_hi:[1,0,1]
	v_pk_fma_f32 v[10:11], v[42:43], v[26:27], v[10:11] op_sel_hi:[1,0,1]
	v_pk_fma_f32 v[8:9], v[44:45], v[28:29], v[8:9] op_sel_hi:[1,0,1]
	v_pk_fma_f32 v[6:7], v[42:43], v[28:29], v[6:7] op_sel_hi:[1,0,1]
	v_pk_fma_f32 v[4:5], v[44:45], v[34:35], v[4:5] op_sel_hi:[1,0,1]
	v_pk_fma_f32 v[2:3], v[42:43], v[34:35], v[2:3] op_sel_hi:[1,0,1]
	s_waitcnt vmcnt(11)
	v_pk_fma_f32 v[16:17], v[48:49], v[30:31], v[16:17] op_sel_hi:[1,0,1]
	v_pk_fma_f32 v[14:15], v[46:47], v[30:31], v[14:15] op_sel_hi:[1,0,1]
	v_pk_fma_f32 v[10:11], v[46:47], v[96:97], v[10:11] op_sel_hi:[1,0,1]
	v_pk_fma_f32 v[12:13], v[48:49], v[96:97], v[12:13] op_sel_hi:[1,0,1]
	v_pk_fma_f32 v[6:7], v[46:47], v[100:101], v[6:7] op_sel_hi:[1,0,1]
	v_pk_fma_f32 v[8:9], v[48:49], v[100:101], v[8:9] op_sel_hi:[1,0,1]
	v_pk_fma_f32 v[2:3], v[46:47], v[104:105], v[2:3] op_sel_hi:[1,0,1]
	v_pk_fma_f32 v[4:5], v[48:49], v[104:105], v[4:5] op_sel_hi:[1,0,1]
	s_waitcnt vmcnt(10)
	v_pk_fma_f32 v[16:17], v[134:135], v[30:31], v[16:17] op_sel:[0,1,0]
	v_pk_fma_f32 v[14:15], v[132:133], v[30:31], v[14:15] op_sel:[0,1,0]
	v_pk_fma_f32 v[12:13], v[134:135], v[96:97], v[12:13] op_sel:[0,1,0]
	v_pk_fma_f32 v[10:11], v[132:133], v[96:97], v[10:11] op_sel:[0,1,0]
	v_pk_fma_f32 v[8:9], v[134:135], v[100:101], v[8:9] op_sel:[0,1,0]
	v_pk_fma_f32 v[6:7], v[132:133], v[100:101], v[6:7] op_sel:[0,1,0]
	v_pk_fma_f32 v[4:5], v[134:135], v[104:105], v[4:5] op_sel:[0,1,0]
	v_pk_fma_f32 v[2:3], v[132:133], v[104:105], v[2:3] op_sel:[0,1,0]
	v_mov_b32_e32 v162, v99
	v_mov_b32_e32 v164, v103
	v_mov_b32_e32 v166, v107
	s_waitcnt vmcnt(9)
	v_pk_fma_f32 v[16:17], v[52:53], v[32:33], v[16:17] op_sel_hi:[1,0,1]
	v_pk_fma_f32 v[14:15], v[50:51], v[32:33], v[14:15] op_sel_hi:[1,0,1]
	v_pk_fma_f32 v[10:11], v[50:51], v[98:99], v[10:11] op_sel_hi:[1,0,1]
	v_pk_fma_f32 v[12:13], v[52:53], v[98:99], v[12:13] op_sel_hi:[1,0,1]
	v_pk_fma_f32 v[6:7], v[50:51], v[102:103], v[6:7] op_sel_hi:[1,0,1]
	v_pk_fma_f32 v[8:9], v[52:53], v[102:103], v[8:9] op_sel_hi:[1,0,1]
	v_pk_fma_f32 v[2:3], v[50:51], v[106:107], v[2:3] op_sel_hi:[1,0,1]
	v_pk_fma_f32 v[4:5], v[52:53], v[106:107], v[4:5] op_sel_hi:[1,0,1]
	s_waitcnt vmcnt(8)
	v_pk_fma_f32 v[16:17], v[138:139], v[156:157], v[16:17] op_sel_hi:[1,0,1]
	v_pk_fma_f32 v[14:15], v[136:137], v[156:157], v[14:15] op_sel_hi:[1,0,1]
	v_pk_fma_f32 v[12:13], v[138:139], v[162:163], v[12:13] op_sel_hi:[1,0,1]
	v_pk_fma_f32 v[10:11], v[136:137], v[162:163], v[10:11] op_sel_hi:[1,0,1]
	v_pk_fma_f32 v[8:9], v[138:139], v[164:165], v[8:9] op_sel_hi:[1,0,1]
	v_pk_fma_f32 v[6:7], v[136:137], v[164:165], v[6:7] op_sel_hi:[1,0,1]
	v_pk_fma_f32 v[4:5], v[138:139], v[166:167], v[4:5] op_sel_hi:[1,0,1]
	v_pk_fma_f32 v[2:3], v[136:137], v[166:167], v[2:3] op_sel_hi:[1,0,1]
	s_waitcnt vmcnt(7)
	v_pk_fma_f32 v[16:17], v[56:57], v[22:23], v[16:17] op_sel_hi:[1,0,1]
	v_pk_fma_f32 v[14:15], v[54:55], v[22:23], v[14:15] op_sel_hi:[1,0,1]
	v_pk_fma_f32 v[10:11], v[54:55], v[108:109], v[10:11] op_sel_hi:[1,0,1]
	v_pk_fma_f32 v[12:13], v[56:57], v[108:109], v[12:13] op_sel_hi:[1,0,1]
	v_pk_fma_f32 v[6:7], v[54:55], v[112:113], v[6:7] op_sel_hi:[1,0,1]
	v_pk_fma_f32 v[8:9], v[56:57], v[112:113], v[8:9] op_sel_hi:[1,0,1]
	v_pk_fma_f32 v[2:3], v[54:55], v[116:117], v[2:3] op_sel_hi:[1,0,1]
	v_pk_fma_f32 v[4:5], v[56:57], v[116:117], v[4:5] op_sel_hi:[1,0,1]
	s_waitcnt vmcnt(6)
	v_pk_fma_f32 v[16:17], v[142:143], v[22:23], v[16:17] op_sel:[0,1,0]
	v_pk_fma_f32 v[14:15], v[140:141], v[22:23], v[14:15] op_sel:[0,1,0]
	v_pk_fma_f32 v[12:13], v[142:143], v[108:109], v[12:13] op_sel:[0,1,0]
	v_pk_fma_f32 v[10:11], v[140:141], v[108:109], v[10:11] op_sel:[0,1,0]
	v_pk_fma_f32 v[8:9], v[142:143], v[112:113], v[8:9] op_sel:[0,1,0]
	v_pk_fma_f32 v[6:7], v[140:141], v[112:113], v[6:7] op_sel:[0,1,0]
	v_pk_fma_f32 v[4:5], v[142:143], v[116:117], v[4:5] op_sel:[0,1,0]
	v_pk_fma_f32 v[2:3], v[140:141], v[116:117], v[2:3] op_sel:[0,1,0]
	v_mov_b32_e32 v168, v111
	v_mov_b32_e32 v170, v115
	v_mov_b32_e32 v172, v119
	s_waitcnt vmcnt(5)
	v_pk_fma_f32 v[16:17], v[60:61], v[24:25], v[16:17] op_sel_hi:[1,0,1]
	v_pk_fma_f32 v[14:15], v[58:59], v[24:25], v[14:15] op_sel_hi:[1,0,1]
	v_pk_fma_f32 v[10:11], v[58:59], v[110:111], v[10:11] op_sel_hi:[1,0,1]
	v_pk_fma_f32 v[12:13], v[60:61], v[110:111], v[12:13] op_sel_hi:[1,0,1]
	v_pk_fma_f32 v[6:7], v[58:59], v[114:115], v[6:7] op_sel_hi:[1,0,1]
	v_pk_fma_f32 v[8:9], v[60:61], v[114:115], v[8:9] op_sel_hi:[1,0,1]
	v_pk_fma_f32 v[2:3], v[58:59], v[118:119], v[2:3] op_sel_hi:[1,0,1]
	v_pk_fma_f32 v[4:5], v[60:61], v[118:119], v[4:5] op_sel_hi:[1,0,1]
	s_waitcnt vmcnt(4)
	v_pk_fma_f32 v[16:17], v[146:147], v[158:159], v[16:17] op_sel_hi:[1,0,1]
	v_pk_fma_f32 v[14:15], v[144:145], v[158:159], v[14:15] op_sel_hi:[1,0,1]
	v_pk_fma_f32 v[12:13], v[146:147], v[168:169], v[12:13] op_sel_hi:[1,0,1]
	v_pk_fma_f32 v[10:11], v[144:145], v[168:169], v[10:11] op_sel_hi:[1,0,1]
	v_pk_fma_f32 v[8:9], v[146:147], v[170:171], v[8:9] op_sel_hi:[1,0,1]
	v_pk_fma_f32 v[6:7], v[144:145], v[170:171], v[6:7] op_sel_hi:[1,0,1]
	v_pk_fma_f32 v[4:5], v[146:147], v[172:173], v[4:5] op_sel_hi:[1,0,1]
	v_pk_fma_f32 v[2:3], v[144:145], v[172:173], v[2:3] op_sel_hi:[1,0,1]
	s_waitcnt vmcnt(3)
	v_pk_fma_f32 v[16:17], v[64:65], v[18:19], v[16:17] op_sel_hi:[1,0,1]
	v_pk_fma_f32 v[14:15], v[62:63], v[18:19], v[14:15] op_sel_hi:[1,0,1]
	v_pk_fma_f32 v[10:11], v[62:63], v[72:73], v[10:11] op_sel_hi:[1,0,1]
	v_pk_fma_f32 v[12:13], v[64:65], v[72:73], v[12:13] op_sel_hi:[1,0,1]
	v_pk_fma_f32 v[6:7], v[62:63], v[120:121], v[6:7] op_sel_hi:[1,0,1]
	v_pk_fma_f32 v[8:9], v[64:65], v[120:121], v[8:9] op_sel_hi:[1,0,1]
	v_pk_fma_f32 v[2:3], v[62:63], v[124:125], v[2:3] op_sel_hi:[1,0,1]
	v_pk_fma_f32 v[4:5], v[64:65], v[124:125], v[4:5] op_sel_hi:[1,0,1]
	s_waitcnt vmcnt(2)
	v_pk_fma_f32 v[16:17], v[150:151], v[18:19], v[16:17] op_sel:[0,1,0]
	v_pk_fma_f32 v[14:15], v[148:149], v[18:19], v[14:15] op_sel:[0,1,0]
	v_pk_fma_f32 v[12:13], v[150:151], v[72:73], v[12:13] op_sel:[0,1,0]
	v_pk_fma_f32 v[10:11], v[148:149], v[72:73], v[10:11] op_sel:[0,1,0]
	v_pk_fma_f32 v[8:9], v[150:151], v[120:121], v[8:9] op_sel:[0,1,0]
	v_pk_fma_f32 v[6:7], v[148:149], v[120:121], v[6:7] op_sel:[0,1,0]
	v_pk_fma_f32 v[4:5], v[150:151], v[124:125], v[4:5] op_sel:[0,1,0]
	v_pk_fma_f32 v[2:3], v[148:149], v[124:125], v[2:3] op_sel:[0,1,0]
	v_mov_b32_e32 v174, v75
	v_mov_b32_e32 v176, v123
	v_mov_b32_e32 v178, v127
	s_waitcnt vmcnt(1)
	v_pk_fma_f32 v[16:17], v[68:69], v[20:21], v[16:17] op_sel_hi:[1,0,1]
	v_pk_fma_f32 v[14:15], v[66:67], v[20:21], v[14:15] op_sel_hi:[1,0,1]
	v_pk_fma_f32 v[10:11], v[66:67], v[74:75], v[10:11] op_sel_hi:[1,0,1]
	v_pk_fma_f32 v[12:13], v[68:69], v[74:75], v[12:13] op_sel_hi:[1,0,1]
	v_pk_fma_f32 v[6:7], v[66:67], v[122:123], v[6:7] op_sel_hi:[1,0,1]
	v_pk_fma_f32 v[8:9], v[68:69], v[122:123], v[8:9] op_sel_hi:[1,0,1]
	v_pk_fma_f32 v[2:3], v[66:67], v[126:127], v[2:3] op_sel_hi:[1,0,1]
	v_pk_fma_f32 v[4:5], v[68:69], v[126:127], v[4:5] op_sel_hi:[1,0,1]
	s_waitcnt vmcnt(0)
	v_pk_fma_f32 v[16:17], v[154:155], v[160:161], v[16:17] op_sel_hi:[1,0,1]
	v_pk_fma_f32 v[14:15], v[152:153], v[160:161], v[14:15] op_sel_hi:[1,0,1]
	v_pk_fma_f32 v[12:13], v[154:155], v[174:175], v[12:13] op_sel_hi:[1,0,1]
	v_pk_fma_f32 v[10:11], v[152:153], v[174:175], v[10:11] op_sel_hi:[1,0,1]
	v_pk_fma_f32 v[8:9], v[154:155], v[176:177], v[8:9] op_sel_hi:[1,0,1]
	v_pk_fma_f32 v[6:7], v[152:153], v[176:177], v[6:7] op_sel_hi:[1,0,1]
	v_pk_fma_f32 v[4:5], v[154:155], v[178:179], v[4:5] op_sel_hi:[1,0,1]
	v_pk_fma_f32 v[2:3], v[152:153], v[178:179], v[2:3] op_sel_hi:[1,0,1]
	s_cbranch_scc0 .LBB0_52
	v_lshlrev_b32_e32 v18, 8, v76
	v_sub_u32_e32 v18, v18, v79
	v_or_b32_e32 v18, v18, v1
	v_add_u32_e32 v20, 15, v76
	v_ashrrev_i32_e32 v19, 31, v18
	v_cmp_gt_u32_e32 vcc, 31, v20
	s_and_saveexec_b64 s[24:25], vcc
	s_cbranch_execz .LBB0_50
	v_readlane_b32 s46, v251, 13
	v_readlane_b32 s47, v251, 14
	s_load_dwordx2 s[46:47], s[46:47], 0x18
	s_waitcnt lgkmcnt(0)
	v_lshl_add_u64 v[20:21], v[18:19], 2, s[46:47]
	global_load_dwordx4 v[20:23], v[20:21], off
	s_waitcnt vmcnt(0)
	v_pk_add_f32 v[16:17], v[16:17], v[22:23]
	v_pk_add_f32 v[14:15], v[14:15], v[20:21]
	v_pk_add_f32 v[12:13], v[12:13], v[22:23]
	v_pk_add_f32 v[10:11], v[10:11], v[20:21]
	v_pk_add_f32 v[8:9], v[8:9], v[22:23]
	v_pk_add_f32 v[6:7], v[6:7], v[20:21]
	v_pk_add_f32 v[4:5], v[4:5], v[22:23]
	v_pk_add_f32 v[2:3], v[2:3], v[20:21]
	s_branch .LBB0_50

.LBB0_417:
	s_lshl_b32 s8, s8, 8
	s_lshl_b32 s10, s9, 8
	s_ashr_i32 s9, s8, 31
	s_ashr_i32 s11, s10, 31
	s_lshl_b64 s[8:9], s[8:9], 12
	s_add_u32 s12, s46, s8
	s_addc_u32 s13, s47, s9
	s_lshl_b64 s[8:9], s[10:11], 1
	s_add_u32 s30, s12, s8
	s_addc_u32 s31, s13, s9
	s_lshl_b64 s[8:9], s[10:11], 2
	v_mov_b32_e32 v136, v143
	v_mov_b32_e32 v138, v142
	s_add_u32 s8, s16, s8
	s_addc_u32 s9, s17, s9
	v_lshl_add_u32 v140, v138, 3, s41
	v_ashrrev_i32_e32 v141, 31, v140
	v_lshl_add_u64 v[138:139], v[140:141], 2, s[8:9]
	global_load_dwordx4 v[148:151], v[138:139], off
	global_load_dwordx4 v[152:155], v[138:139], off offset:16
	global_load_dwordx4 v[216:219], v[138:139], off
	global_load_dwordx4 v[220:223], v[138:139], off offset:16
	global_load_dwordx4 v[224:227], v[138:139], off offset:512
	global_load_dwordx4 v[228:231], v[138:139], off offset:528
	v_lshl_add_u32 v141, v136, 11, s45
	v_add_u32_e32 v136, v140, v141
	s_waitcnt vmcnt(0)
	v_pk_add_f32 v[124:125], v[124:125], v[148:149]
	s_nop 0
	v_mul_f32_e32 v124, 0xbfb8aa3b, v124
	v_pk_add_f32 v[126:127], v[126:127], v[150:151]
	v_mul_f32_e32 v125, 0xbfb8aa3b, v125
	v_exp_f32_e32 v124, v124
	v_mul_f32_e32 v126, 0xbfb8aa3b, v126
	v_exp_f32_e32 v125, v125
	v_mul_f32_e32 v127, 0xbfb8aa3b, v127
	v_exp_f32_e32 v126, v126
	v_exp_f32_e32 v127, v127
	v_add_f32_e32 v124, 1.0, v124
	v_add_f32_e32 v125, 1.0, v125
	v_div_scale_f32 v148, s[8:9], v124, v124, 1.0
	v_pk_add_f32 v[120:121], v[120:121], v[152:153]
	v_add_f32_e32 v126, 1.0, v126
	v_div_scale_f32 v150, s[8:9], v125, v125, 1.0
	v_rcp_f32_e32 v158, v148
	v_mul_f32_e32 v120, 0xbfb8aa3b, v120
	v_add_f32_e32 v127, 1.0, v127
	v_div_scale_f32 v152, s[10:11], v126, v126, 1.0
	v_rcp_f32_e32 v159, v150
	v_pk_add_f32 v[122:123], v[122:123], v[154:155]
	v_exp_f32_e32 v120, v120
	v_div_scale_f32 v154, s[12:13], v127, v127, 1.0
	v_rcp_f32_e32 v160, v152
	v_rcp_f32_e32 v161, v154
	v_fma_f32 v163, -v148, v158, 1.0
	v_div_scale_f32 v149, vcc, 1.0, v124, 1.0
	v_fma_f32 v164, -v150, v159, 1.0
	v_fmac_f32_e32 v158, v163, v158
	v_add_f32_e32 v120, 1.0, v120
	v_div_scale_f32 v151, s[8:9], 1.0, v125, 1.0
	v_fma_f32 v165, -v152, v160, 1.0
	v_fmac_f32_e32 v159, v164, v159
	v_mul_f32_e32 v163, v149, v158
	v_div_scale_f32 v153, s[10:11], 1.0, v126, 1.0
	v_div_scale_f32 v156, s[14:15], v120, v120, 1.0
	v_fma_f32 v166, -v154, v161, 1.0
	v_fmac_f32_e32 v160, v165, v160
	v_mul_f32_e32 v164, v151, v159
	v_fma_f32 v168, -v148, v163, v149
	v_mul_f32_e32 v121, 0xbfb8aa3b, v121
	v_div_scale_f32 v155, s[12:13], 1.0, v127, 1.0
	v_rcp_f32_e32 v162, v156
	v_fmac_f32_e32 v161, v166, v161
	v_mul_f32_e32 v165, v153, v160
	v_fma_f32 v169, -v150, v164, v151
	v_fmac_f32_e32 v163, v168, v158
	v_exp_f32_e32 v121, v121
	v_mul_f32_e32 v166, v155, v161
	v_fma_f32 v170, -v152, v165, v153
	v_fmac_f32_e32 v164, v169, v159
	v_fma_f32 v148, -v148, v163, v149
	v_fma_f32 v171, -v154, v166, v155
	v_fmac_f32_e32 v165, v170, v160
	v_fma_f32 v149, -v150, v164, v151
	v_div_fmas_f32 v148, v148, v158, v163
	s_mov_b64 vcc, s[8:9]
	v_fmac_f32_e32 v166, v171, v161
	v_fma_f32 v150, -v152, v165, v153
	v_div_fixup_f32 v124, v148, v124, 1.0
	v_div_fmas_f32 v148, v149, v159, v164
	s_mov_b64 vcc, s[10:11]
	v_fma_f32 v167, -v156, v162, 1.0
	v_fma_f32 v151, -v154, v166, v155
	v_div_fixup_f32 v125, v148, v125, 1.0
	v_div_fmas_f32 v148, v150, v160, v165
	s_mov_b64 vcc, s[12:13]
	v_add_f32_e32 v121, 1.0, v121
	v_div_scale_f32 v157, s[14:15], 1.0, v120, 1.0
	v_fmac_f32_e32 v162, v167, v162
	v_div_fixup_f32 v126, v148, v126, 1.0
	v_div_fmas_f32 v148, v151, v161, v166
	v_mul_f32_e32 v167, v157, v162
	v_div_fixup_f32 v127, v148, v127, 1.0
	v_div_scale_f32 v148, s[8:9], v121, v121, 1.0
	v_fma_f32 v172, -v156, v167, v157
	v_rcp_f32_e32 v149, v148
	v_fmac_f32_e32 v167, v172, v162
	v_fma_f32 v152, -v156, v167, v157
	s_mov_b64 vcc, s[14:15]
	v_div_fmas_f32 v150, v152, v162, v167
	v_mul_f32_e32 v122, 0xbfb8aa3b, v122
	v_div_fixup_f32 v150, v150, v120, 1.0
	v_fma_f32 v120, -v148, v149, 1.0
	v_exp_f32_e32 v122, v122
	v_fmac_f32_e32 v149, v120, v149
	v_div_scale_f32 v120, vcc, 1.0, v121, 1.0
	v_mul_f32_e32 v151, v120, v149
	v_fma_f32 v152, -v148, v151, v120
	v_fmac_f32_e32 v151, v152, v149
	v_add_f32_e32 v122, 1.0, v122
	v_fma_f32 v120, -v148, v151, v120
	v_div_scale_f32 v148, s[8:9], v122, v122, 1.0
	v_rcp_f32_e32 v152, v148
	v_div_fmas_f32 v120, v120, v149, v151
	v_mul_f32_e32 v123, 0xbfb8aa3b, v123
	v_div_fixup_f32 v149, v120, v121, 1.0
	v_fma_f32 v120, -v148, v152, 1.0
	v_exp_f32_e32 v123, v123
	v_fmac_f32_e32 v152, v120, v152
	v_div_scale_f32 v120, vcc, 1.0, v122, 1.0
	v_mul_f32_e32 v121, v120, v152
	v_fma_f32 v151, -v148, v121, v120
	v_fmac_f32_e32 v121, v151, v152
	v_add_f32_e32 v123, 1.0, v123
	v_fma_f32 v120, -v148, v121, v120
	v_div_scale_f32 v148, s[8:9], v123, v123, 1.0
	v_rcp_f32_e32 v151, v148
	v_div_fmas_f32 v120, v120, v152, v121
	v_div_fixup_f32 v152, v120, v122, 1.0
	v_fma_f32 v120, -v148, v151, 1.0
	v_fmac_f32_e32 v151, v120, v151
	v_div_scale_f32 v120, vcc, 1.0, v123, 1.0
	v_mul_f32_e32 v121, v120, v151
	v_fma_f32 v122, -v148, v121, v120
	v_fmac_f32_e32 v121, v122, v151
	v_fma_f32 v120, -v148, v121, v120
	v_div_fmas_f32 v120, v120, v151, v121
	v_div_fixup_f32 v123, v120, v123, 1.0
	v_cvt_pk_bf16_f32 v120, v124, v125
	v_lshl_add_u64 v[124:125], v[136:137], 1, s[30:31]
	v_cvt_pk_bf16_f32 v121, v126, v127
	v_cvt_pk_bf16_f32 v122, v150, v149
	v_cvt_pk_bf16_f32 v123, v152, v123
	global_store_dwordx4 v[124:125], v[120:123], off
	s_nop 1
	v_mov_b64_e32 v[122:123], v[224:225]
	v_mov_b64_e32 v[124:125], v[226:227]
	s_nop 0
	v_mov_b64_e32 v[148:149], v[228:229]
	v_mov_b64_e32 v[150:151], v[230:231]
	v_add_u32_e32 v120, 0x80, v140
	v_add_u32_e32 v136, v120, v141
	v_pk_add_f32 v[116:117], v[116:117], v[122:123]
	s_nop 0
	v_mul_f32_e32 v116, 0xbfb8aa3b, v116
	v_mul_f32_e32 v117, 0xbfb8aa3b, v117
	v_exp_f32_e32 v116, v116
	v_exp_f32_e32 v117, v117
	v_pk_add_f32 v[118:119], v[118:119], v[124:125]
	v_pk_add_f32 v[112:113], v[112:113], v[148:149]
	v_mul_f32_e32 v118, 0xbfb8aa3b, v118
	v_add_f32_e32 v116, 1.0, v116
	v_exp_f32_e32 v118, v118
	v_add_f32_e32 v117, 1.0, v117
	v_div_scale_f32 v121, s[8:9], v116, v116, 1.0
	v_div_scale_f32 v123, s[8:9], v117, v117, 1.0
	v_rcp_f32_e32 v126, v121
	v_rcp_f32_e32 v127, v123
	v_add_f32_e32 v118, 1.0, v118
	v_div_scale_f32 v125, s[10:11], v118, v118, 1.0
	v_fma_f32 v154, -v121, v126, 1.0
	v_div_scale_f32 v122, vcc, 1.0, v116, 1.0
	v_rcp_f32_e32 v152, v125
	v_fma_f32 v155, -v123, v127, 1.0
	v_fmac_f32_e32 v126, v154, v126
	v_mul_f32_e32 v119, 0xbfb8aa3b, v119
	v_div_scale_f32 v124, s[8:9], 1.0, v117, 1.0
	v_fmac_f32_e32 v127, v155, v127
	v_mul_f32_e32 v154, v122, v126
	v_exp_f32_e32 v119, v119
	v_mul_f32_e32 v155, v124, v127
	v_fma_f32 v157, -v121, v154, v122
	v_fma_f32 v158, -v123, v155, v124
	v_fmac_f32_e32 v154, v157, v126
	v_fma_f32 v156, -v125, v152, 1.0
	v_fmac_f32_e32 v155, v158, v127
	v_fma_f32 v121, -v121, v154, v122
	v_div_scale_f32 v153, s[10:11], 1.0, v118, 1.0
	v_fmac_f32_e32 v152, v156, v152
	v_fma_f32 v122, -v123, v155, v124
	v_div_fmas_f32 v121, v121, v126, v154
	s_mov_b64 vcc, s[8:9]
	v_add_f32_e32 v119, 1.0, v119
	v_mul_f32_e32 v156, v153, v152
	v_div_fixup_f32 v116, v121, v116, 1.0
	v_div_fmas_f32 v121, v122, v127, v155
	v_div_scale_f32 v122, s[8:9], v119, v119, 1.0
	v_div_fixup_f32 v117, v121, v117, 1.0
	v_fma_f32 v121, -v125, v156, v153
	v_rcp_f32_e32 v123, v122
	v_fmac_f32_e32 v156, v121, v152
	v_fma_f32 v121, -v125, v156, v153
	s_mov_b64 vcc, s[10:11]
	v_div_fmas_f32 v121, v121, v152, v156
	v_mul_f32_e32 v112, 0xbfb8aa3b, v112
	v_div_fixup_f32 v118, v121, v118, 1.0
	v_fma_f32 v121, -v122, v123, 1.0
	v_exp_f32_e32 v112, v112
	v_fmac_f32_e32 v123, v121, v123
	v_div_scale_f32 v121, vcc, 1.0, v119, 1.0
	v_mul_f32_e32 v124, v121, v123
	v_fma_f32 v125, -v122, v124, v121
	v_fmac_f32_e32 v124, v125, v123
	v_add_f32_e32 v112, 1.0, v112
	v_fma_f32 v121, -v122, v124, v121
	v_div_scale_f32 v122, s[8:9], v112, v112, 1.0
	v_rcp_f32_e32 v125, v122
	v_div_fmas_f32 v121, v121, v123, v124
	v_mul_f32_e32 v113, 0xbfb8aa3b, v113
	v_div_fixup_f32 v119, v121, v119, 1.0
	v_fma_f32 v121, -v122, v125, 1.0
	v_exp_f32_e32 v113, v113
	v_fmac_f32_e32 v125, v121, v125
	v_div_scale_f32 v121, vcc, 1.0, v112, 1.0
	v_mul_f32_e32 v123, v121, v125
	v_fma_f32 v124, -v122, v123, v121
	v_fmac_f32_e32 v123, v124, v125
	v_add_f32_e32 v113, 1.0, v113
	v_fma_f32 v121, -v122, v123, v121
	v_div_scale_f32 v122, s[8:9], v113, v113, 1.0
	v_rcp_f32_e32 v124, v122
	v_pk_add_f32 v[114:115], v[114:115], v[150:151]
	v_div_fmas_f32 v121, v121, v125, v123
	v_mul_f32_e32 v114, 0xbfb8aa3b, v114
	v_div_fixup_f32 v121, v121, v112, 1.0
	v_fma_f32 v112, -v122, v124, 1.0
	v_exp_f32_e32 v114, v114
	v_fmac_f32_e32 v124, v112, v124
	v_div_scale_f32 v112, vcc, 1.0, v113, 1.0
	v_mul_f32_e32 v123, v112, v124
	v_fma_f32 v125, -v122, v123, v112
	v_fmac_f32_e32 v123, v125, v124
	v_add_f32_e32 v114, 1.0, v114
	v_fma_f32 v112, -v122, v123, v112
	v_div_scale_f32 v122, s[8:9], v114, v114, 1.0
	v_rcp_f32_e32 v125, v122
	v_div_fmas_f32 v112, v112, v124, v123
	v_mul_f32_e32 v115, 0xbfb8aa3b, v115
	v_div_fixup_f32 v123, v112, v113, 1.0
	v_fma_f32 v112, -v122, v125, 1.0
	v_exp_f32_e32 v115, v115
	v_fmac_f32_e32 v125, v112, v125
	v_div_scale_f32 v112, vcc, 1.0, v114, 1.0
	v_mul_f32_e32 v113, v112, v125
	v_fma_f32 v124, -v122, v113, v112
	v_fmac_f32_e32 v113, v124, v125
	v_add_f32_e32 v115, 1.0, v115
	v_fma_f32 v112, -v122, v113, v112
	v_div_scale_f32 v122, s[8:9], v115, v115, 1.0
	v_rcp_f32_e32 v124, v122
	v_div_fmas_f32 v112, v112, v125, v113
	v_div_fixup_f32 v125, v112, v114, 1.0
	v_fma_f32 v112, -v122, v124, 1.0
	v_fmac_f32_e32 v124, v112, v124
	v_div_scale_f32 v112, vcc, 1.0, v115, 1.0
	v_mul_f32_e32 v113, v112, v124
	v_fma_f32 v114, -v122, v113, v112
	v_fmac_f32_e32 v113, v114, v124
	v_fma_f32 v112, -v122, v113, v112
	v_div_fmas_f32 v112, v112, v124, v113
	v_div_fixup_f32 v115, v112, v115, 1.0
	v_cvt_pk_bf16_f32 v112, v116, v117
	v_lshl_add_u64 v[116:117], v[136:137], 1, s[30:31]
	v_cvt_pk_bf16_f32 v113, v118, v119
	v_cvt_pk_bf16_f32 v114, v121, v123
	v_cvt_pk_bf16_f32 v115, v125, v115
	global_store_dwordx4 v[116:117], v[112:115], off
	s_nop 1
	v_mov_b64_e32 v[112:113], v[216:217]
	v_mov_b64_e32 v[114:115], v[218:219]
	v_mov_b64_e32 v[116:117], v[220:221]
	v_mov_b64_e32 v[118:119], v[222:223]
	v_add_u32_e32 v121, 0x8000, v141
	v_add_u32_e32 v136, v121, v140
	v_pk_add_f32 v[108:109], v[108:109], v[112:113]
	s_nop 0
	v_mul_f32_e32 v108, 0xbfb8aa3b, v108
	v_exp_f32_e32 v108, v108
	v_mul_f32_e32 v109, 0xbfb8aa3b, v109
	v_pk_add_f32 v[110:111], v[110:111], v[114:115]
	v_exp_f32_e32 v109, v109
	v_add_f32_e32 v108, 1.0, v108
	v_div_scale_f32 v112, s[8:9], v108, v108, 1.0
	v_rcp_f32_e32 v113, v112
	v_add_f32_e32 v109, 1.0, v109
	v_mul_f32_e32 v110, 0xbfb8aa3b, v110
	v_exp_f32_e32 v110, v110
	v_fma_f32 v114, -v112, v113, 1.0
	v_fmac_f32_e32 v113, v114, v113
	v_div_scale_f32 v114, vcc, 1.0, v108, 1.0
	v_mul_f32_e32 v115, v114, v113
	v_fma_f32 v122, -v112, v115, v114
	v_fmac_f32_e32 v115, v122, v113
	v_fma_f32 v112, -v112, v115, v114
	v_div_scale_f32 v114, s[8:9], v109, v109, 1.0
	v_rcp_f32_e32 v122, v114
	v_div_fmas_f32 v112, v112, v113, v115
	v_div_fixup_f32 v108, v112, v108, 1.0
	v_add_f32_e32 v110, 1.0, v110
	v_fma_f32 v112, -v114, v122, 1.0
	v_fmac_f32_e32 v122, v112, v122
	v_div_scale_f32 v112, vcc, 1.0, v109, 1.0
	v_mul_f32_e32 v113, v112, v122
	v_fma_f32 v115, -v114, v113, v112
	v_fmac_f32_e32 v113, v115, v122
	v_fma_f32 v112, -v114, v113, v112
	v_div_scale_f32 v114, s[8:9], v110, v110, 1.0
	v_rcp_f32_e32 v115, v114
	v_div_fmas_f32 v112, v112, v122, v113
	v_mul_f32_e32 v111, 0xbfb8aa3b, v111
	v_div_fixup_f32 v109, v112, v109, 1.0
	v_fma_f32 v112, -v114, v115, 1.0
	v_exp_f32_e32 v111, v111
	v_fmac_f32_e32 v115, v112, v115
	v_div_scale_f32 v112, vcc, 1.0, v110, 1.0
	v_mul_f32_e32 v113, v112, v115
	v_fma_f32 v122, -v114, v113, v112
	v_fmac_f32_e32 v113, v122, v115
	v_add_f32_e32 v111, 1.0, v111
	v_fma_f32 v112, -v114, v113, v112
	v_div_scale_f32 v114, s[8:9], v111, v111, 1.0
	v_rcp_f32_e32 v122, v114
	v_pk_add_f32 v[104:105], v[104:105], v[116:117]
	v_div_fmas_f32 v112, v112, v115, v113
	v_mul_f32_e32 v104, 0xbfb8aa3b, v104
	v_div_fixup_f32 v110, v112, v110, 1.0
	v_fma_f32 v112, -v114, v122, 1.0
	v_exp_f32_e32 v104, v104
	v_fmac_f32_e32 v122, v112, v122
	v_div_scale_f32 v112, vcc, 1.0, v111, 1.0
	v_mul_f32_e32 v113, v112, v122
	v_fma_f32 v115, -v114, v113, v112
	v_fmac_f32_e32 v113, v115, v122
	v_add_f32_e32 v104, 1.0, v104
	v_fma_f32 v112, -v114, v113, v112
	v_div_scale_f32 v114, s[8:9], v104, v104, 1.0
	v_rcp_f32_e32 v115, v114
	v_div_fmas_f32 v112, v112, v122, v113
	v_mul_f32_e32 v105, 0xbfb8aa3b, v105
	v_div_fixup_f32 v111, v112, v111, 1.0
	v_fma_f32 v112, -v114, v115, 1.0
	v_exp_f32_e32 v105, v105
	v_fmac_f32_e32 v115, v112, v115
	v_div_scale_f32 v112, vcc, 1.0, v104, 1.0
	v_mul_f32_e32 v113, v112, v115
	v_fma_f32 v116, -v114, v113, v112
	v_fmac_f32_e32 v113, v116, v115
	v_add_f32_e32 v105, 1.0, v105
	v_fma_f32 v112, -v114, v113, v112
	v_div_scale_f32 v114, s[8:9], v105, v105, 1.0
	v_rcp_f32_e32 v116, v114
	v_pk_add_f32 v[106:107], v[106:107], v[118:119]
	v_div_fmas_f32 v112, v112, v115, v113
	v_mul_f32_e32 v106, 0xbfb8aa3b, v106
	v_div_fixup_f32 v112, v112, v104, 1.0
	v_fma_f32 v104, -v114, v116, 1.0
	v_exp_f32_e32 v106, v106
	v_fmac_f32_e32 v116, v104, v116
	v_div_scale_f32 v104, vcc, 1.0, v105, 1.0
	v_mul_f32_e32 v113, v104, v116
	v_fma_f32 v115, -v114, v113, v104
	v_fmac_f32_e32 v113, v115, v116
	v_add_f32_e32 v106, 1.0, v106
	v_fma_f32 v104, -v114, v113, v104
	v_div_scale_f32 v114, s[8:9], v106, v106, 1.0
	v_rcp_f32_e32 v115, v114
	v_div_fmas_f32 v104, v104, v116, v113
	v_mul_f32_e32 v107, 0xbfb8aa3b, v107
	v_div_fixup_f32 v113, v104, v105, 1.0
	v_fma_f32 v104, -v114, v115, 1.0
	v_exp_f32_e32 v107, v107
	v_fmac_f32_e32 v115, v104, v115
	v_div_scale_f32 v104, vcc, 1.0, v106, 1.0
	v_mul_f32_e32 v105, v104, v115
	v_fma_f32 v116, -v114, v105, v104
	v_fmac_f32_e32 v105, v116, v115
	v_add_f32_e32 v107, 1.0, v107
	v_fma_f32 v104, -v114, v105, v104
	v_div_scale_f32 v114, s[8:9], v107, v107, 1.0
	v_rcp_f32_e32 v116, v114
	v_div_fmas_f32 v104, v104, v115, v105
	v_div_fixup_f32 v115, v104, v106, 1.0
	v_fma_f32 v104, -v114, v116, 1.0
	v_fmac_f32_e32 v116, v104, v116
	v_div_scale_f32 v104, vcc, 1.0, v107, 1.0
	v_mul_f32_e32 v105, v104, v116
	v_fma_f32 v106, -v114, v105, v104
	v_fmac_f32_e32 v105, v106, v116
	v_fma_f32 v104, -v114, v105, v104
	v_div_fmas_f32 v104, v104, v116, v105
	v_div_fixup_f32 v107, v104, v107, 1.0
	v_cvt_pk_bf16_f32 v104, v108, v109
	v_lshl_add_u64 v[108:109], v[136:137], 1, s[30:31]
	v_cvt_pk_bf16_f32 v105, v110, v111
	v_cvt_pk_bf16_f32 v106, v112, v113
	v_cvt_pk_bf16_f32 v107, v115, v107
	global_store_dwordx4 v[108:109], v[104:107], off
	s_nop 1
	v_mov_b64_e32 v[104:105], v[224:225]
	v_mov_b64_e32 v[106:107], v[226:227]
	s_nop 0
	v_mov_b64_e32 v[108:109], v[228:229]
	v_mov_b64_e32 v[110:111], v[230:231]
	v_add_u32_e32 v136, v120, v121
	v_pk_add_f32 v[100:101], v[100:101], v[104:105]
	s_nop 0
	v_mul_f32_e32 v100, 0xbfb8aa3b, v100
	v_exp_f32_e32 v100, v100
	v_mul_f32_e32 v101, 0xbfb8aa3b, v101
	v_pk_add_f32 v[102:103], v[102:103], v[106:107]
	v_exp_f32_e32 v101, v101
	v_add_f32_e32 v100, 1.0, v100
	v_div_scale_f32 v104, s[8:9], v100, v100, 1.0
	v_rcp_f32_e32 v105, v104
	v_add_f32_e32 v101, 1.0, v101
	v_mul_f32_e32 v102, 0xbfb8aa3b, v102
	v_exp_f32_e32 v102, v102
	v_fma_f32 v106, -v104, v105, 1.0
	v_fmac_f32_e32 v105, v106, v105
	v_div_scale_f32 v106, vcc, 1.0, v100, 1.0
	v_mul_f32_e32 v107, v106, v105
	v_fma_f32 v112, -v104, v107, v106
	v_fmac_f32_e32 v107, v112, v105
	v_fma_f32 v104, -v104, v107, v106
	v_div_scale_f32 v106, s[8:9], v101, v101, 1.0
	v_rcp_f32_e32 v112, v106
	v_div_fmas_f32 v104, v104, v105, v107
	v_div_fixup_f32 v100, v104, v100, 1.0
	v_add_f32_e32 v102, 1.0, v102
	v_fma_f32 v104, -v106, v112, 1.0
	v_fmac_f32_e32 v112, v104, v112
	v_div_scale_f32 v104, vcc, 1.0, v101, 1.0
	v_mul_f32_e32 v105, v104, v112
	v_fma_f32 v107, -v106, v105, v104
	v_fmac_f32_e32 v105, v107, v112
	v_fma_f32 v104, -v106, v105, v104
	v_div_scale_f32 v106, s[8:9], v102, v102, 1.0
	v_rcp_f32_e32 v107, v106
	v_div_fmas_f32 v104, v104, v112, v105
	v_mul_f32_e32 v103, 0xbfb8aa3b, v103
	v_div_fixup_f32 v101, v104, v101, 1.0
	v_fma_f32 v104, -v106, v107, 1.0
	v_exp_f32_e32 v103, v103
	v_fmac_f32_e32 v107, v104, v107
	v_div_scale_f32 v104, vcc, 1.0, v102, 1.0
	v_mul_f32_e32 v105, v104, v107
	v_fma_f32 v112, -v106, v105, v104
	v_fmac_f32_e32 v105, v112, v107
	v_add_f32_e32 v103, 1.0, v103
	v_fma_f32 v104, -v106, v105, v104
	v_div_scale_f32 v106, s[8:9], v103, v103, 1.0
	v_rcp_f32_e32 v112, v106
	v_pk_add_f32 v[96:97], v[96:97], v[108:109]
	v_div_fmas_f32 v104, v104, v107, v105
	v_mul_f32_e32 v96, 0xbfb8aa3b, v96
	v_div_fixup_f32 v102, v104, v102, 1.0
	v_fma_f32 v104, -v106, v112, 1.0
	v_exp_f32_e32 v96, v96
	v_fmac_f32_e32 v112, v104, v112
	v_div_scale_f32 v104, vcc, 1.0, v103, 1.0
	v_mul_f32_e32 v105, v104, v112
	v_fma_f32 v107, -v106, v105, v104
	v_fmac_f32_e32 v105, v107, v112
	v_add_f32_e32 v96, 1.0, v96
	v_fma_f32 v104, -v106, v105, v104
	v_div_scale_f32 v106, s[8:9], v96, v96, 1.0
	v_rcp_f32_e32 v107, v106
	v_div_fmas_f32 v104, v104, v112, v105
	v_mul_f32_e32 v97, 0xbfb8aa3b, v97
	v_div_fixup_f32 v103, v104, v103, 1.0
	v_fma_f32 v104, -v106, v107, 1.0
	v_exp_f32_e32 v97, v97
	v_fmac_f32_e32 v107, v104, v107
	v_div_scale_f32 v104, vcc, 1.0, v96, 1.0
	v_mul_f32_e32 v105, v104, v107
	v_fma_f32 v108, -v106, v105, v104
	v_fmac_f32_e32 v105, v108, v107
	v_add_f32_e32 v97, 1.0, v97
	v_fma_f32 v104, -v106, v105, v104
	v_div_scale_f32 v106, s[8:9], v97, v97, 1.0
	v_rcp_f32_e32 v108, v106
	v_pk_add_f32 v[98:99], v[98:99], v[110:111]
	v_div_fmas_f32 v104, v104, v107, v105
	v_mul_f32_e32 v98, 0xbfb8aa3b, v98
	v_div_fixup_f32 v104, v104, v96, 1.0
	v_fma_f32 v96, -v106, v108, 1.0
	v_exp_f32_e32 v98, v98
	v_fmac_f32_e32 v108, v96, v108
	v_div_scale_f32 v96, vcc, 1.0, v97, 1.0
	v_mul_f32_e32 v105, v96, v108
	v_fma_f32 v107, -v106, v105, v96
	v_fmac_f32_e32 v105, v107, v108
	v_add_f32_e32 v98, 1.0, v98
	v_fma_f32 v96, -v106, v105, v96
	v_div_scale_f32 v106, s[8:9], v98, v98, 1.0
	v_rcp_f32_e32 v107, v106
	v_div_fmas_f32 v96, v96, v108, v105
	v_mul_f32_e32 v99, 0xbfb8aa3b, v99
	v_div_fixup_f32 v105, v96, v97, 1.0
	v_fma_f32 v96, -v106, v107, 1.0
	v_exp_f32_e32 v99, v99
	v_fmac_f32_e32 v107, v96, v107
	v_div_scale_f32 v96, vcc, 1.0, v98, 1.0
	v_mul_f32_e32 v97, v96, v107
	v_fma_f32 v108, -v106, v97, v96
	v_fmac_f32_e32 v97, v108, v107
	v_add_f32_e32 v99, 1.0, v99
	v_fma_f32 v96, -v106, v97, v96
	v_div_scale_f32 v106, s[8:9], v99, v99, 1.0
	v_rcp_f32_e32 v108, v106
	v_div_fmas_f32 v96, v96, v107, v97
	v_div_fixup_f32 v107, v96, v98, 1.0
	v_fma_f32 v96, -v106, v108, 1.0
	v_fmac_f32_e32 v108, v96, v108
	v_div_scale_f32 v96, vcc, 1.0, v99, 1.0
	v_mul_f32_e32 v97, v96, v108
	v_fma_f32 v98, -v106, v97, v96
	v_fmac_f32_e32 v97, v98, v108
	v_fma_f32 v96, -v106, v97, v96
	v_div_fmas_f32 v96, v96, v108, v97
	v_div_fixup_f32 v99, v96, v99, 1.0
	v_cvt_pk_bf16_f32 v96, v100, v101
	v_lshl_add_u64 v[100:101], v[136:137], 1, s[30:31]
	v_cvt_pk_bf16_f32 v97, v102, v103
	v_cvt_pk_bf16_f32 v98, v104, v105
	v_cvt_pk_bf16_f32 v99, v107, v99
	global_store_dwordx4 v[100:101], v[96:99], off
	s_nop 1
	v_mov_b64_e32 v[96:97], v[216:217]
	v_mov_b64_e32 v[98:99], v[218:219]
	v_mov_b64_e32 v[100:101], v[220:221]
	v_mov_b64_e32 v[102:103], v[222:223]
	v_add_u32_e32 v104, 0x10000, v141
	v_add_u32_e32 v136, v104, v140
	v_pk_add_f32 v[92:93], v[92:93], v[96:97]
	s_nop 0
	v_mul_f32_e32 v92, 0xbfb8aa3b, v92
	v_exp_f32_e32 v92, v92
	v_mul_f32_e32 v93, 0xbfb8aa3b, v93
	v_pk_add_f32 v[94:95], v[94:95], v[98:99]
	v_exp_f32_e32 v93, v93
	v_add_f32_e32 v92, 1.0, v92
	v_div_scale_f32 v96, s[8:9], v92, v92, 1.0
	v_rcp_f32_e32 v97, v96
	v_add_f32_e32 v93, 1.0, v93
	v_mul_f32_e32 v94, 0xbfb8aa3b, v94
	v_exp_f32_e32 v94, v94
	v_fma_f32 v98, -v96, v97, 1.0
	v_fmac_f32_e32 v97, v98, v97
	v_div_scale_f32 v98, vcc, 1.0, v92, 1.0
	v_mul_f32_e32 v99, v98, v97
	v_fma_f32 v105, -v96, v99, v98
	v_fmac_f32_e32 v99, v105, v97
	v_fma_f32 v96, -v96, v99, v98
	v_div_scale_f32 v98, s[8:9], v93, v93, 1.0
	v_rcp_f32_e32 v105, v98
	v_div_fmas_f32 v96, v96, v97, v99
	v_div_fixup_f32 v92, v96, v92, 1.0
	v_add_f32_e32 v94, 1.0, v94
	v_fma_f32 v96, -v98, v105, 1.0
	v_fmac_f32_e32 v105, v96, v105
	v_div_scale_f32 v96, vcc, 1.0, v93, 1.0
	v_mul_f32_e32 v97, v96, v105
	v_fma_f32 v99, -v98, v97, v96
	v_fmac_f32_e32 v97, v99, v105
	v_fma_f32 v96, -v98, v97, v96
	v_div_scale_f32 v98, s[8:9], v94, v94, 1.0
	v_rcp_f32_e32 v99, v98
	v_div_fmas_f32 v96, v96, v105, v97
	v_mul_f32_e32 v95, 0xbfb8aa3b, v95
	v_div_fixup_f32 v93, v96, v93, 1.0
	v_fma_f32 v96, -v98, v99, 1.0
	v_exp_f32_e32 v95, v95
	v_fmac_f32_e32 v99, v96, v99
	v_div_scale_f32 v96, vcc, 1.0, v94, 1.0
	v_mul_f32_e32 v97, v96, v99
	v_fma_f32 v105, -v98, v97, v96
	v_fmac_f32_e32 v97, v105, v99
	v_add_f32_e32 v95, 1.0, v95
	v_fma_f32 v96, -v98, v97, v96
	v_div_scale_f32 v98, s[8:9], v95, v95, 1.0
	v_rcp_f32_e32 v105, v98
	v_pk_add_f32 v[88:89], v[88:89], v[100:101]
	v_div_fmas_f32 v96, v96, v99, v97
	v_mul_f32_e32 v88, 0xbfb8aa3b, v88
	v_div_fixup_f32 v94, v96, v94, 1.0
	v_fma_f32 v96, -v98, v105, 1.0
	v_exp_f32_e32 v88, v88
	v_fmac_f32_e32 v105, v96, v105
	v_div_scale_f32 v96, vcc, 1.0, v95, 1.0
	v_mul_f32_e32 v97, v96, v105
	v_fma_f32 v99, -v98, v97, v96
	v_fmac_f32_e32 v97, v99, v105
	v_add_f32_e32 v88, 1.0, v88
	v_fma_f32 v96, -v98, v97, v96
	v_div_scale_f32 v98, s[8:9], v88, v88, 1.0
	v_rcp_f32_e32 v99, v98
	v_div_fmas_f32 v96, v96, v105, v97
	v_mul_f32_e32 v89, 0xbfb8aa3b, v89
	v_div_fixup_f32 v95, v96, v95, 1.0
	v_fma_f32 v96, -v98, v99, 1.0
	v_exp_f32_e32 v89, v89
	v_fmac_f32_e32 v99, v96, v99
	v_div_scale_f32 v96, vcc, 1.0, v88, 1.0
	v_mul_f32_e32 v97, v96, v99
	v_fma_f32 v100, -v98, v97, v96
	v_fmac_f32_e32 v97, v100, v99
	v_add_f32_e32 v89, 1.0, v89
	v_fma_f32 v96, -v98, v97, v96
	v_div_scale_f32 v98, s[8:9], v89, v89, 1.0
	v_rcp_f32_e32 v100, v98
	v_pk_add_f32 v[90:91], v[90:91], v[102:103]
	v_div_fmas_f32 v96, v96, v99, v97
	v_mul_f32_e32 v90, 0xbfb8aa3b, v90
	v_div_fixup_f32 v96, v96, v88, 1.0
	v_fma_f32 v88, -v98, v100, 1.0
	v_exp_f32_e32 v90, v90
	v_fmac_f32_e32 v100, v88, v100
	v_div_scale_f32 v88, vcc, 1.0, v89, 1.0
	v_mul_f32_e32 v97, v88, v100
	v_fma_f32 v99, -v98, v97, v88
	v_fmac_f32_e32 v97, v99, v100
	v_add_f32_e32 v90, 1.0, v90
	v_fma_f32 v88, -v98, v97, v88
	v_div_scale_f32 v98, s[8:9], v90, v90, 1.0
	v_rcp_f32_e32 v99, v98
	v_div_fmas_f32 v88, v88, v100, v97
	v_mul_f32_e32 v91, 0xbfb8aa3b, v91
	v_div_fixup_f32 v97, v88, v89, 1.0
	v_fma_f32 v88, -v98, v99, 1.0
	v_exp_f32_e32 v91, v91
	v_fmac_f32_e32 v99, v88, v99
	v_div_scale_f32 v88, vcc, 1.0, v90, 1.0
	v_mul_f32_e32 v89, v88, v99
	v_fma_f32 v100, -v98, v89, v88
	v_fmac_f32_e32 v89, v100, v99
	v_add_f32_e32 v91, 1.0, v91
	v_fma_f32 v88, -v98, v89, v88
	v_div_scale_f32 v98, s[8:9], v91, v91, 1.0
	v_rcp_f32_e32 v100, v98
	v_div_fmas_f32 v88, v88, v99, v89
	v_div_fixup_f32 v99, v88, v90, 1.0
	v_fma_f32 v88, -v98, v100, 1.0
	v_fmac_f32_e32 v100, v88, v100
	v_div_scale_f32 v88, vcc, 1.0, v91, 1.0
	v_mul_f32_e32 v89, v88, v100
	v_fma_f32 v90, -v98, v89, v88
	v_fmac_f32_e32 v89, v90, v100
	v_fma_f32 v88, -v98, v89, v88
	v_div_fmas_f32 v88, v88, v100, v89
	v_div_fixup_f32 v91, v88, v91, 1.0
	v_cvt_pk_bf16_f32 v88, v92, v93
	v_lshl_add_u64 v[92:93], v[136:137], 1, s[30:31]
	v_cvt_pk_bf16_f32 v89, v94, v95
	v_cvt_pk_bf16_f32 v90, v96, v97
	v_cvt_pk_bf16_f32 v91, v99, v91
	global_store_dwordx4 v[92:93], v[88:91], off
	s_nop 1
	v_mov_b64_e32 v[88:89], v[224:225]
	v_mov_b64_e32 v[90:91], v[226:227]
	s_nop 0
	v_mov_b64_e32 v[92:93], v[228:229]
	v_mov_b64_e32 v[94:95], v[230:231]
	v_add_u32_e32 v136, v120, v104
	v_pk_add_f32 v[84:85], v[84:85], v[88:89]
	s_nop 0
	v_mul_f32_e32 v84, 0xbfb8aa3b, v84
	v_exp_f32_e32 v84, v84
	v_mul_f32_e32 v85, 0xbfb8aa3b, v85
	v_pk_add_f32 v[86:87], v[86:87], v[90:91]
	v_exp_f32_e32 v85, v85
	v_add_f32_e32 v84, 1.0, v84
	v_div_scale_f32 v88, s[8:9], v84, v84, 1.0
	v_rcp_f32_e32 v89, v88
	v_add_f32_e32 v85, 1.0, v85
	v_mul_f32_e32 v86, 0xbfb8aa3b, v86
	v_exp_f32_e32 v86, v86
	v_fma_f32 v90, -v88, v89, 1.0
	v_fmac_f32_e32 v89, v90, v89
	v_div_scale_f32 v90, vcc, 1.0, v84, 1.0
	v_mul_f32_e32 v91, v90, v89
	v_fma_f32 v96, -v88, v91, v90
	v_fmac_f32_e32 v91, v96, v89
	v_fma_f32 v88, -v88, v91, v90
	v_div_scale_f32 v90, s[8:9], v85, v85, 1.0
	v_rcp_f32_e32 v96, v90
	v_div_fmas_f32 v88, v88, v89, v91
	v_div_fixup_f32 v84, v88, v84, 1.0
	v_add_f32_e32 v86, 1.0, v86
	v_fma_f32 v88, -v90, v96, 1.0
	v_fmac_f32_e32 v96, v88, v96
	v_div_scale_f32 v88, vcc, 1.0, v85, 1.0
	v_mul_f32_e32 v89, v88, v96
	v_fma_f32 v91, -v90, v89, v88
	v_fmac_f32_e32 v89, v91, v96
	v_fma_f32 v88, -v90, v89, v88
	v_div_scale_f32 v90, s[8:9], v86, v86, 1.0
	v_rcp_f32_e32 v91, v90
	v_div_fmas_f32 v88, v88, v96, v89
	v_mul_f32_e32 v87, 0xbfb8aa3b, v87
	v_div_fixup_f32 v85, v88, v85, 1.0
	v_fma_f32 v88, -v90, v91, 1.0
	v_exp_f32_e32 v87, v87
	v_fmac_f32_e32 v91, v88, v91
	v_div_scale_f32 v88, vcc, 1.0, v86, 1.0
	v_mul_f32_e32 v89, v88, v91
	v_fma_f32 v96, -v90, v89, v88
	v_fmac_f32_e32 v89, v96, v91
	v_add_f32_e32 v87, 1.0, v87
	v_fma_f32 v88, -v90, v89, v88
	v_div_scale_f32 v90, s[8:9], v87, v87, 1.0
	v_rcp_f32_e32 v96, v90
	v_pk_add_f32 v[80:81], v[80:81], v[92:93]
	v_div_fmas_f32 v88, v88, v91, v89
	v_mul_f32_e32 v80, 0xbfb8aa3b, v80
	v_div_fixup_f32 v86, v88, v86, 1.0
	v_fma_f32 v88, -v90, v96, 1.0
	v_exp_f32_e32 v80, v80
	v_fmac_f32_e32 v96, v88, v96
	v_div_scale_f32 v88, vcc, 1.0, v87, 1.0
	v_mul_f32_e32 v89, v88, v96
	v_fma_f32 v91, -v90, v89, v88
	v_fmac_f32_e32 v89, v91, v96
	v_add_f32_e32 v80, 1.0, v80
	v_fma_f32 v88, -v90, v89, v88
	v_div_scale_f32 v90, s[8:9], v80, v80, 1.0
	v_rcp_f32_e32 v91, v90
	v_div_fmas_f32 v88, v88, v96, v89
	v_mul_f32_e32 v81, 0xbfb8aa3b, v81
	v_div_fixup_f32 v87, v88, v87, 1.0
	v_fma_f32 v88, -v90, v91, 1.0
	v_exp_f32_e32 v81, v81
	v_fmac_f32_e32 v91, v88, v91
	v_div_scale_f32 v88, vcc, 1.0, v80, 1.0
	v_mul_f32_e32 v89, v88, v91
	v_fma_f32 v92, -v90, v89, v88
	v_fmac_f32_e32 v89, v92, v91
	v_add_f32_e32 v81, 1.0, v81
	v_fma_f32 v88, -v90, v89, v88
	v_div_scale_f32 v90, s[8:9], v81, v81, 1.0
	v_rcp_f32_e32 v92, v90
	v_pk_add_f32 v[82:83], v[82:83], v[94:95]
	v_div_fmas_f32 v88, v88, v91, v89
	v_mul_f32_e32 v82, 0xbfb8aa3b, v82
	v_div_fixup_f32 v88, v88, v80, 1.0
	v_fma_f32 v80, -v90, v92, 1.0
	v_exp_f32_e32 v82, v82
	v_fmac_f32_e32 v92, v80, v92
	v_div_scale_f32 v80, vcc, 1.0, v81, 1.0
	v_mul_f32_e32 v89, v80, v92
	v_fma_f32 v91, -v90, v89, v80
	v_fmac_f32_e32 v89, v91, v92
	v_add_f32_e32 v82, 1.0, v82
	v_fma_f32 v80, -v90, v89, v80
	v_div_scale_f32 v90, s[8:9], v82, v82, 1.0
	v_rcp_f32_e32 v91, v90
	v_div_fmas_f32 v80, v80, v92, v89
	v_mul_f32_e32 v83, 0xbfb8aa3b, v83
	v_div_fixup_f32 v89, v80, v81, 1.0
	v_fma_f32 v80, -v90, v91, 1.0
	v_exp_f32_e32 v83, v83
	v_fmac_f32_e32 v91, v80, v91
	v_div_scale_f32 v80, vcc, 1.0, v82, 1.0
	v_mul_f32_e32 v81, v80, v91
	v_fma_f32 v92, -v90, v81, v80
	v_fmac_f32_e32 v81, v92, v91
	v_add_f32_e32 v83, 1.0, v83
	v_fma_f32 v80, -v90, v81, v80
	v_div_scale_f32 v90, s[8:9], v83, v83, 1.0
	v_rcp_f32_e32 v92, v90
	v_div_fmas_f32 v80, v80, v91, v81
	v_div_fixup_f32 v91, v80, v82, 1.0
	v_fma_f32 v80, -v90, v92, 1.0
	v_fmac_f32_e32 v92, v80, v92
	v_div_scale_f32 v80, vcc, 1.0, v83, 1.0
	v_mul_f32_e32 v81, v80, v92
	v_fma_f32 v82, -v90, v81, v80
	v_fmac_f32_e32 v81, v82, v92
	v_fma_f32 v80, -v90, v81, v80
	v_div_fmas_f32 v80, v80, v92, v81
	v_div_fixup_f32 v83, v80, v83, 1.0
	v_cvt_pk_bf16_f32 v80, v84, v85
	v_lshl_add_u64 v[84:85], v[136:137], 1, s[30:31]
	v_cvt_pk_bf16_f32 v81, v86, v87
	v_cvt_pk_bf16_f32 v82, v88, v89
	v_cvt_pk_bf16_f32 v83, v91, v83
	global_store_dwordx4 v[84:85], v[80:83], off
	s_nop 1
	v_mov_b64_e32 v[80:81], v[216:217]
	v_mov_b64_e32 v[82:83], v[218:219]
	v_mov_b64_e32 v[84:85], v[220:221]
	v_mov_b64_e32 v[86:87], v[222:223]
	v_add_u32_e32 v88, 0x18000, v141
	v_add_u32_e32 v136, v88, v140
	v_pk_add_f32 v[76:77], v[76:77], v[80:81]
	s_nop 0
	v_mul_f32_e32 v76, 0xbfb8aa3b, v76
	v_exp_f32_e32 v76, v76
	v_mul_f32_e32 v77, 0xbfb8aa3b, v77
	v_pk_add_f32 v[78:79], v[78:79], v[82:83]
	v_exp_f32_e32 v77, v77
	v_add_f32_e32 v76, 1.0, v76
	v_div_scale_f32 v80, s[8:9], v76, v76, 1.0
	v_rcp_f32_e32 v81, v80
	v_add_f32_e32 v77, 1.0, v77
	v_mul_f32_e32 v78, 0xbfb8aa3b, v78
	v_exp_f32_e32 v78, v78
	v_fma_f32 v82, -v80, v81, 1.0
	v_fmac_f32_e32 v81, v82, v81
	v_div_scale_f32 v82, vcc, 1.0, v76, 1.0
	v_mul_f32_e32 v83, v82, v81
	v_fma_f32 v89, -v80, v83, v82
	v_fmac_f32_e32 v83, v89, v81
	v_fma_f32 v80, -v80, v83, v82
	v_div_scale_f32 v82, s[8:9], v77, v77, 1.0
	v_rcp_f32_e32 v89, v82
	v_div_fmas_f32 v80, v80, v81, v83
	v_div_fixup_f32 v76, v80, v76, 1.0
	v_add_f32_e32 v78, 1.0, v78
	v_fma_f32 v80, -v82, v89, 1.0
	v_fmac_f32_e32 v89, v80, v89
	v_div_scale_f32 v80, vcc, 1.0, v77, 1.0
	v_mul_f32_e32 v81, v80, v89
	v_fma_f32 v83, -v82, v81, v80
	v_fmac_f32_e32 v81, v83, v89
	v_fma_f32 v80, -v82, v81, v80
	v_div_scale_f32 v82, s[8:9], v78, v78, 1.0
	v_rcp_f32_e32 v83, v82
	v_div_fmas_f32 v80, v80, v89, v81
	v_mul_f32_e32 v79, 0xbfb8aa3b, v79
	v_div_fixup_f32 v77, v80, v77, 1.0
	v_fma_f32 v80, -v82, v83, 1.0
	v_exp_f32_e32 v79, v79
	v_fmac_f32_e32 v83, v80, v83
	v_div_scale_f32 v80, vcc, 1.0, v78, 1.0
	v_mul_f32_e32 v81, v80, v83
	v_fma_f32 v89, -v82, v81, v80
	v_fmac_f32_e32 v81, v89, v83
	v_add_f32_e32 v79, 1.0, v79
	v_fma_f32 v80, -v82, v81, v80
	v_div_scale_f32 v82, s[8:9], v79, v79, 1.0
	v_rcp_f32_e32 v89, v82
	v_pk_add_f32 v[72:73], v[72:73], v[84:85]
	v_div_fmas_f32 v80, v80, v83, v81
	v_mul_f32_e32 v72, 0xbfb8aa3b, v72
	v_div_fixup_f32 v78, v80, v78, 1.0
	v_fma_f32 v80, -v82, v89, 1.0
	v_exp_f32_e32 v72, v72
	v_fmac_f32_e32 v89, v80, v89
	v_div_scale_f32 v80, vcc, 1.0, v79, 1.0
	v_mul_f32_e32 v81, v80, v89
	v_fma_f32 v83, -v82, v81, v80
	v_fmac_f32_e32 v81, v83, v89
	v_add_f32_e32 v72, 1.0, v72
	v_fma_f32 v80, -v82, v81, v80
	v_div_scale_f32 v82, s[8:9], v72, v72, 1.0
	v_rcp_f32_e32 v83, v82
	v_div_fmas_f32 v80, v80, v89, v81
	v_mul_f32_e32 v73, 0xbfb8aa3b, v73
	v_div_fixup_f32 v79, v80, v79, 1.0
	v_fma_f32 v80, -v82, v83, 1.0
	v_exp_f32_e32 v73, v73
	v_fmac_f32_e32 v83, v80, v83
	v_div_scale_f32 v80, vcc, 1.0, v72, 1.0
	v_mul_f32_e32 v81, v80, v83
	v_fma_f32 v84, -v82, v81, v80
	v_fmac_f32_e32 v81, v84, v83
	v_add_f32_e32 v73, 1.0, v73
	v_fma_f32 v80, -v82, v81, v80
	v_div_scale_f32 v82, s[8:9], v73, v73, 1.0
	v_rcp_f32_e32 v84, v82
	v_pk_add_f32 v[74:75], v[74:75], v[86:87]
	v_div_fmas_f32 v80, v80, v83, v81
	v_mul_f32_e32 v74, 0xbfb8aa3b, v74
	v_div_fixup_f32 v80, v80, v72, 1.0
	v_fma_f32 v72, -v82, v84, 1.0
	v_exp_f32_e32 v74, v74
	v_fmac_f32_e32 v84, v72, v84
	v_div_scale_f32 v72, vcc, 1.0, v73, 1.0
	v_mul_f32_e32 v81, v72, v84
	v_fma_f32 v83, -v82, v81, v72
	v_fmac_f32_e32 v81, v83, v84
	v_add_f32_e32 v74, 1.0, v74
	v_fma_f32 v72, -v82, v81, v72
	v_div_scale_f32 v82, s[8:9], v74, v74, 1.0
	v_rcp_f32_e32 v83, v82
	v_div_fmas_f32 v72, v72, v84, v81
	v_mul_f32_e32 v75, 0xbfb8aa3b, v75
	v_div_fixup_f32 v81, v72, v73, 1.0
	v_fma_f32 v72, -v82, v83, 1.0
	v_exp_f32_e32 v75, v75
	v_fmac_f32_e32 v83, v72, v83
	v_div_scale_f32 v72, vcc, 1.0, v74, 1.0
	v_mul_f32_e32 v73, v72, v83
	v_fma_f32 v84, -v82, v73, v72
	v_fmac_f32_e32 v73, v84, v83
	v_add_f32_e32 v75, 1.0, v75
	v_fma_f32 v72, -v82, v73, v72
	v_div_scale_f32 v82, s[8:9], v75, v75, 1.0
	v_rcp_f32_e32 v84, v82
	v_div_fmas_f32 v72, v72, v83, v73
	v_div_fixup_f32 v83, v72, v74, 1.0
	v_fma_f32 v72, -v82, v84, 1.0
	v_fmac_f32_e32 v84, v72, v84
	v_div_scale_f32 v72, vcc, 1.0, v75, 1.0
	v_mul_f32_e32 v73, v72, v84
	v_fma_f32 v74, -v82, v73, v72
	v_fmac_f32_e32 v73, v74, v84
	v_fma_f32 v72, -v82, v73, v72
	v_div_fmas_f32 v72, v72, v84, v73
	v_div_fixup_f32 v75, v72, v75, 1.0
	v_cvt_pk_bf16_f32 v72, v76, v77
	v_lshl_add_u64 v[76:77], v[136:137], 1, s[30:31]
	v_cvt_pk_bf16_f32 v73, v78, v79
	v_cvt_pk_bf16_f32 v74, v80, v81
	v_cvt_pk_bf16_f32 v75, v83, v75
	global_store_dwordx4 v[76:77], v[72:75], off
	s_nop 1
	v_mov_b64_e32 v[72:73], v[224:225]
	v_mov_b64_e32 v[74:75], v[226:227]
	s_nop 0
	v_mov_b64_e32 v[76:77], v[228:229]
	v_mov_b64_e32 v[78:79], v[230:231]
	v_add_u32_e32 v136, v120, v88
	v_pk_add_f32 v[68:69], v[68:69], v[72:73]
	s_nop 0
	v_mul_f32_e32 v68, 0xbfb8aa3b, v68
	v_exp_f32_e32 v68, v68
	v_mul_f32_e32 v69, 0xbfb8aa3b, v69
	v_pk_add_f32 v[70:71], v[70:71], v[74:75]
	v_exp_f32_e32 v69, v69
	v_add_f32_e32 v68, 1.0, v68
	v_div_scale_f32 v72, s[8:9], v68, v68, 1.0
	v_rcp_f32_e32 v73, v72
	v_add_f32_e32 v69, 1.0, v69
	v_mul_f32_e32 v70, 0xbfb8aa3b, v70
	v_exp_f32_e32 v70, v70
	v_fma_f32 v74, -v72, v73, 1.0
	v_fmac_f32_e32 v73, v74, v73
	v_div_scale_f32 v74, vcc, 1.0, v68, 1.0
	v_mul_f32_e32 v75, v74, v73
	v_fma_f32 v80, -v72, v75, v74
	v_fmac_f32_e32 v75, v80, v73
	v_fma_f32 v72, -v72, v75, v74
	v_div_scale_f32 v74, s[8:9], v69, v69, 1.0
	v_rcp_f32_e32 v80, v74
	v_div_fmas_f32 v72, v72, v73, v75
	v_div_fixup_f32 v68, v72, v68, 1.0
	v_add_f32_e32 v70, 1.0, v70
	v_fma_f32 v72, -v74, v80, 1.0
	v_fmac_f32_e32 v80, v72, v80
	v_div_scale_f32 v72, vcc, 1.0, v69, 1.0
	v_mul_f32_e32 v73, v72, v80
	v_fma_f32 v75, -v74, v73, v72
	v_fmac_f32_e32 v73, v75, v80
	v_fma_f32 v72, -v74, v73, v72
	v_div_scale_f32 v74, s[8:9], v70, v70, 1.0
	v_rcp_f32_e32 v75, v74
	v_div_fmas_f32 v72, v72, v80, v73
	v_mul_f32_e32 v71, 0xbfb8aa3b, v71
	v_div_fixup_f32 v69, v72, v69, 1.0
	v_fma_f32 v72, -v74, v75, 1.0
	v_exp_f32_e32 v71, v71
	v_fmac_f32_e32 v75, v72, v75
	v_div_scale_f32 v72, vcc, 1.0, v70, 1.0
	v_mul_f32_e32 v73, v72, v75
	v_fma_f32 v80, -v74, v73, v72
	v_fmac_f32_e32 v73, v80, v75
	v_add_f32_e32 v71, 1.0, v71
	v_fma_f32 v72, -v74, v73, v72
	v_div_scale_f32 v74, s[8:9], v71, v71, 1.0
	v_rcp_f32_e32 v80, v74
	v_pk_add_f32 v[64:65], v[64:65], v[76:77]
	v_div_fmas_f32 v72, v72, v75, v73
	v_mul_f32_e32 v64, 0xbfb8aa3b, v64
	v_div_fixup_f32 v70, v72, v70, 1.0
	v_fma_f32 v72, -v74, v80, 1.0
	v_exp_f32_e32 v64, v64
	v_fmac_f32_e32 v80, v72, v80
	v_div_scale_f32 v72, vcc, 1.0, v71, 1.0
	v_mul_f32_e32 v73, v72, v80
	v_fma_f32 v75, -v74, v73, v72
	v_fmac_f32_e32 v73, v75, v80
	v_add_f32_e32 v64, 1.0, v64
	v_fma_f32 v72, -v74, v73, v72
	v_div_scale_f32 v74, s[8:9], v64, v64, 1.0
	v_rcp_f32_e32 v75, v74
	v_div_fmas_f32 v72, v72, v80, v73
	v_mul_f32_e32 v65, 0xbfb8aa3b, v65
	v_div_fixup_f32 v71, v72, v71, 1.0
	v_fma_f32 v72, -v74, v75, 1.0
	v_exp_f32_e32 v65, v65
	v_fmac_f32_e32 v75, v72, v75
	v_div_scale_f32 v72, vcc, 1.0, v64, 1.0
	v_mul_f32_e32 v73, v72, v75
	v_fma_f32 v76, -v74, v73, v72
	v_fmac_f32_e32 v73, v76, v75
	v_add_f32_e32 v65, 1.0, v65
	v_fma_f32 v72, -v74, v73, v72
	v_div_scale_f32 v74, s[8:9], v65, v65, 1.0
	v_rcp_f32_e32 v76, v74
	v_pk_add_f32 v[66:67], v[66:67], v[78:79]
	v_div_fmas_f32 v72, v72, v75, v73
	v_mul_f32_e32 v66, 0xbfb8aa3b, v66
	v_div_fixup_f32 v72, v72, v64, 1.0
	v_fma_f32 v64, -v74, v76, 1.0
	v_exp_f32_e32 v66, v66
	v_fmac_f32_e32 v76, v64, v76
	v_div_scale_f32 v64, vcc, 1.0, v65, 1.0
	v_mul_f32_e32 v73, v64, v76
	v_fma_f32 v75, -v74, v73, v64
	v_fmac_f32_e32 v73, v75, v76
	v_add_f32_e32 v66, 1.0, v66
	v_fma_f32 v64, -v74, v73, v64
	v_div_scale_f32 v74, s[8:9], v66, v66, 1.0
	v_rcp_f32_e32 v75, v74
	v_div_fmas_f32 v64, v64, v76, v73
	v_mul_f32_e32 v67, 0xbfb8aa3b, v67
	v_div_fixup_f32 v73, v64, v65, 1.0
	v_fma_f32 v64, -v74, v75, 1.0
	v_exp_f32_e32 v67, v67
	v_fmac_f32_e32 v75, v64, v75
	v_div_scale_f32 v64, vcc, 1.0, v66, 1.0
	v_mul_f32_e32 v65, v64, v75
	v_fma_f32 v76, -v74, v65, v64
	v_fmac_f32_e32 v65, v76, v75
	v_add_f32_e32 v67, 1.0, v67
	v_fma_f32 v64, -v74, v65, v64
	v_div_scale_f32 v74, s[8:9], v67, v67, 1.0
	v_rcp_f32_e32 v76, v74
	v_div_fmas_f32 v64, v64, v75, v65
	v_div_fixup_f32 v75, v64, v66, 1.0
	v_fma_f32 v64, -v74, v76, 1.0
	v_fmac_f32_e32 v76, v64, v76
	v_div_scale_f32 v64, vcc, 1.0, v67, 1.0
	v_mul_f32_e32 v65, v64, v76
	v_fma_f32 v66, -v74, v65, v64
	v_fmac_f32_e32 v65, v66, v76
	v_fma_f32 v64, -v74, v65, v64
	v_div_fmas_f32 v64, v64, v76, v65
	v_div_fixup_f32 v67, v64, v67, 1.0
	v_cvt_pk_bf16_f32 v64, v68, v69
	v_lshl_add_u64 v[68:69], v[136:137], 1, s[30:31]
	v_cvt_pk_bf16_f32 v65, v70, v71
	v_cvt_pk_bf16_f32 v66, v72, v73
	v_cvt_pk_bf16_f32 v67, v75, v67
	global_store_dwordx4 v[68:69], v[64:67], off
	s_nop 1
	v_mov_b64_e32 v[64:65], v[216:217]
	v_mov_b64_e32 v[66:67], v[218:219]
	v_mov_b64_e32 v[68:69], v[220:221]
	v_mov_b64_e32 v[70:71], v[222:223]
	v_add_u32_e32 v72, 0x40000, v141
	v_add_u32_e32 v136, v72, v140
	v_pk_add_f32 v[60:61], v[60:61], v[64:65]
	s_nop 0
	v_mul_f32_e32 v60, 0xbfb8aa3b, v60
	v_exp_f32_e32 v60, v60
	v_mul_f32_e32 v61, 0xbfb8aa3b, v61
	v_pk_add_f32 v[62:63], v[62:63], v[66:67]
	v_exp_f32_e32 v61, v61
	v_add_f32_e32 v60, 1.0, v60
	v_div_scale_f32 v64, s[8:9], v60, v60, 1.0
	v_rcp_f32_e32 v65, v64
	v_add_f32_e32 v61, 1.0, v61
	v_mul_f32_e32 v62, 0xbfb8aa3b, v62
	v_exp_f32_e32 v62, v62
	v_fma_f32 v66, -v64, v65, 1.0
	v_fmac_f32_e32 v65, v66, v65
	v_div_scale_f32 v66, vcc, 1.0, v60, 1.0
	v_mul_f32_e32 v67, v66, v65
	v_fma_f32 v73, -v64, v67, v66
	v_fmac_f32_e32 v67, v73, v65
	v_fma_f32 v64, -v64, v67, v66
	v_div_scale_f32 v66, s[8:9], v61, v61, 1.0
	v_rcp_f32_e32 v73, v66
	v_div_fmas_f32 v64, v64, v65, v67
	v_div_fixup_f32 v60, v64, v60, 1.0
	v_add_f32_e32 v62, 1.0, v62
	v_fma_f32 v64, -v66, v73, 1.0
	v_fmac_f32_e32 v73, v64, v73
	v_div_scale_f32 v64, vcc, 1.0, v61, 1.0
	v_mul_f32_e32 v65, v64, v73
	v_fma_f32 v67, -v66, v65, v64
	v_fmac_f32_e32 v65, v67, v73
	v_fma_f32 v64, -v66, v65, v64
	v_div_scale_f32 v66, s[8:9], v62, v62, 1.0
	v_rcp_f32_e32 v67, v66
	v_div_fmas_f32 v64, v64, v73, v65
	v_mul_f32_e32 v63, 0xbfb8aa3b, v63
	v_div_fixup_f32 v61, v64, v61, 1.0
	v_fma_f32 v64, -v66, v67, 1.0
	v_exp_f32_e32 v63, v63
	v_fmac_f32_e32 v67, v64, v67
	v_div_scale_f32 v64, vcc, 1.0, v62, 1.0
	v_mul_f32_e32 v65, v64, v67
	v_fma_f32 v73, -v66, v65, v64
	v_fmac_f32_e32 v65, v73, v67
	v_add_f32_e32 v63, 1.0, v63
	v_fma_f32 v64, -v66, v65, v64
	v_div_scale_f32 v66, s[8:9], v63, v63, 1.0
	v_rcp_f32_e32 v73, v66
	v_pk_add_f32 v[56:57], v[56:57], v[68:69]
	v_div_fmas_f32 v64, v64, v67, v65
	v_mul_f32_e32 v56, 0xbfb8aa3b, v56
	v_div_fixup_f32 v62, v64, v62, 1.0
	v_fma_f32 v64, -v66, v73, 1.0
	v_exp_f32_e32 v56, v56
	v_fmac_f32_e32 v73, v64, v73
	v_div_scale_f32 v64, vcc, 1.0, v63, 1.0
	v_mul_f32_e32 v65, v64, v73
	v_fma_f32 v67, -v66, v65, v64
	v_fmac_f32_e32 v65, v67, v73
	v_add_f32_e32 v56, 1.0, v56
	v_fma_f32 v64, -v66, v65, v64
	v_div_scale_f32 v66, s[8:9], v56, v56, 1.0
	v_rcp_f32_e32 v67, v66
	v_div_fmas_f32 v64, v64, v73, v65
	v_mul_f32_e32 v57, 0xbfb8aa3b, v57
	v_div_fixup_f32 v63, v64, v63, 1.0
	v_fma_f32 v64, -v66, v67, 1.0
	v_exp_f32_e32 v57, v57
	v_fmac_f32_e32 v67, v64, v67
	v_div_scale_f32 v64, vcc, 1.0, v56, 1.0
	v_mul_f32_e32 v65, v64, v67
	v_fma_f32 v68, -v66, v65, v64
	v_fmac_f32_e32 v65, v68, v67
	v_add_f32_e32 v57, 1.0, v57
	v_fma_f32 v64, -v66, v65, v64
	v_div_scale_f32 v66, s[8:9], v57, v57, 1.0
	v_rcp_f32_e32 v68, v66
	v_pk_add_f32 v[58:59], v[58:59], v[70:71]
	v_div_fmas_f32 v64, v64, v67, v65
	v_mul_f32_e32 v58, 0xbfb8aa3b, v58
	v_div_fixup_f32 v64, v64, v56, 1.0
	v_fma_f32 v56, -v66, v68, 1.0
	v_exp_f32_e32 v58, v58
	v_fmac_f32_e32 v68, v56, v68
	v_div_scale_f32 v56, vcc, 1.0, v57, 1.0
	v_mul_f32_e32 v65, v56, v68
	v_fma_f32 v67, -v66, v65, v56
	v_fmac_f32_e32 v65, v67, v68
	v_add_f32_e32 v58, 1.0, v58
	v_fma_f32 v56, -v66, v65, v56
	v_div_scale_f32 v66, s[8:9], v58, v58, 1.0
	v_rcp_f32_e32 v67, v66
	v_div_fmas_f32 v56, v56, v68, v65
	v_mul_f32_e32 v59, 0xbfb8aa3b, v59
	v_div_fixup_f32 v65, v56, v57, 1.0
	v_fma_f32 v56, -v66, v67, 1.0
	v_exp_f32_e32 v59, v59
	v_fmac_f32_e32 v67, v56, v67
	v_div_scale_f32 v56, vcc, 1.0, v58, 1.0
	v_mul_f32_e32 v57, v56, v67
	v_fma_f32 v68, -v66, v57, v56
	v_fmac_f32_e32 v57, v68, v67
	v_add_f32_e32 v59, 1.0, v59
	v_fma_f32 v56, -v66, v57, v56
	v_div_scale_f32 v66, s[8:9], v59, v59, 1.0
	v_rcp_f32_e32 v68, v66
	v_div_fmas_f32 v56, v56, v67, v57
	v_div_fixup_f32 v67, v56, v58, 1.0
	v_fma_f32 v56, -v66, v68, 1.0
	v_fmac_f32_e32 v68, v56, v68
	v_div_scale_f32 v56, vcc, 1.0, v59, 1.0
	v_mul_f32_e32 v57, v56, v68
	v_fma_f32 v58, -v66, v57, v56
	v_fmac_f32_e32 v57, v58, v68
	v_fma_f32 v56, -v66, v57, v56
	v_div_fmas_f32 v56, v56, v68, v57
	v_div_fixup_f32 v59, v56, v59, 1.0
	v_cvt_pk_bf16_f32 v56, v60, v61
	v_lshl_add_u64 v[60:61], v[136:137], 1, s[30:31]
	v_cvt_pk_bf16_f32 v57, v62, v63
	v_cvt_pk_bf16_f32 v58, v64, v65
	v_cvt_pk_bf16_f32 v59, v67, v59
	global_store_dwordx4 v[60:61], v[56:59], off
	s_nop 1
	v_mov_b64_e32 v[56:57], v[224:225]
	v_mov_b64_e32 v[58:59], v[226:227]
	s_nop 0
	v_mov_b64_e32 v[60:61], v[228:229]
	v_mov_b64_e32 v[62:63], v[230:231]
	v_add_u32_e32 v136, v120, v72
	v_pk_add_f32 v[52:53], v[52:53], v[56:57]
	s_nop 0
	v_mul_f32_e32 v52, 0xbfb8aa3b, v52
	v_exp_f32_e32 v52, v52
	v_mul_f32_e32 v53, 0xbfb8aa3b, v53
	v_pk_add_f32 v[54:55], v[54:55], v[58:59]
	v_exp_f32_e32 v53, v53
	v_add_f32_e32 v52, 1.0, v52
	v_div_scale_f32 v56, s[8:9], v52, v52, 1.0
	v_rcp_f32_e32 v57, v56
	v_add_f32_e32 v53, 1.0, v53
	v_mul_f32_e32 v54, 0xbfb8aa3b, v54
	v_exp_f32_e32 v54, v54
	v_fma_f32 v58, -v56, v57, 1.0
	v_fmac_f32_e32 v57, v58, v57
	v_div_scale_f32 v58, vcc, 1.0, v52, 1.0
	v_mul_f32_e32 v59, v58, v57
	v_fma_f32 v64, -v56, v59, v58
	v_fmac_f32_e32 v59, v64, v57
	v_fma_f32 v56, -v56, v59, v58
	v_div_scale_f32 v58, s[8:9], v53, v53, 1.0
	v_rcp_f32_e32 v64, v58
	v_div_fmas_f32 v56, v56, v57, v59
	v_div_fixup_f32 v52, v56, v52, 1.0
	v_add_f32_e32 v54, 1.0, v54
	v_fma_f32 v56, -v58, v64, 1.0
	v_fmac_f32_e32 v64, v56, v64
	v_div_scale_f32 v56, vcc, 1.0, v53, 1.0
	v_mul_f32_e32 v57, v56, v64
	v_fma_f32 v59, -v58, v57, v56
	v_fmac_f32_e32 v57, v59, v64
	v_fma_f32 v56, -v58, v57, v56
	v_div_scale_f32 v58, s[8:9], v54, v54, 1.0
	v_rcp_f32_e32 v59, v58
	v_div_fmas_f32 v56, v56, v64, v57
	v_mul_f32_e32 v55, 0xbfb8aa3b, v55
	v_div_fixup_f32 v53, v56, v53, 1.0
	v_fma_f32 v56, -v58, v59, 1.0
	v_exp_f32_e32 v55, v55
	v_fmac_f32_e32 v59, v56, v59
	v_div_scale_f32 v56, vcc, 1.0, v54, 1.0
	v_mul_f32_e32 v57, v56, v59
	v_fma_f32 v64, -v58, v57, v56
	v_fmac_f32_e32 v57, v64, v59
	v_add_f32_e32 v55, 1.0, v55
	v_fma_f32 v56, -v58, v57, v56
	v_div_scale_f32 v58, s[8:9], v55, v55, 1.0
	v_rcp_f32_e32 v64, v58
	v_pk_add_f32 v[48:49], v[48:49], v[60:61]
	v_div_fmas_f32 v56, v56, v59, v57
	v_mul_f32_e32 v48, 0xbfb8aa3b, v48
	v_div_fixup_f32 v54, v56, v54, 1.0
	v_fma_f32 v56, -v58, v64, 1.0
	v_exp_f32_e32 v48, v48
	v_fmac_f32_e32 v64, v56, v64
	v_div_scale_f32 v56, vcc, 1.0, v55, 1.0
	v_mul_f32_e32 v57, v56, v64
	v_fma_f32 v59, -v58, v57, v56
	v_fmac_f32_e32 v57, v59, v64
	v_add_f32_e32 v48, 1.0, v48
	v_fma_f32 v56, -v58, v57, v56
	v_div_scale_f32 v58, s[8:9], v48, v48, 1.0
	v_rcp_f32_e32 v59, v58
	v_div_fmas_f32 v56, v56, v64, v57
	v_mul_f32_e32 v49, 0xbfb8aa3b, v49
	v_div_fixup_f32 v55, v56, v55, 1.0
	v_fma_f32 v56, -v58, v59, 1.0
	v_exp_f32_e32 v49, v49
	v_fmac_f32_e32 v59, v56, v59
	v_div_scale_f32 v56, vcc, 1.0, v48, 1.0
	v_mul_f32_e32 v57, v56, v59
	v_fma_f32 v60, -v58, v57, v56
	v_fmac_f32_e32 v57, v60, v59
	v_add_f32_e32 v49, 1.0, v49
	v_fma_f32 v56, -v58, v57, v56
	v_div_scale_f32 v58, s[8:9], v49, v49, 1.0
	v_rcp_f32_e32 v60, v58
	v_pk_add_f32 v[50:51], v[50:51], v[62:63]
	v_div_fmas_f32 v56, v56, v59, v57
	v_mul_f32_e32 v50, 0xbfb8aa3b, v50
	v_div_fixup_f32 v56, v56, v48, 1.0
	v_fma_f32 v48, -v58, v60, 1.0
	v_exp_f32_e32 v50, v50
	v_fmac_f32_e32 v60, v48, v60
	v_div_scale_f32 v48, vcc, 1.0, v49, 1.0
	v_mul_f32_e32 v57, v48, v60
	v_fma_f32 v59, -v58, v57, v48
	v_fmac_f32_e32 v57, v59, v60
	v_add_f32_e32 v50, 1.0, v50
	v_fma_f32 v48, -v58, v57, v48
	v_div_scale_f32 v58, s[8:9], v50, v50, 1.0
	v_rcp_f32_e32 v59, v58
	v_div_fmas_f32 v48, v48, v60, v57
	v_mul_f32_e32 v51, 0xbfb8aa3b, v51
	v_div_fixup_f32 v57, v48, v49, 1.0
	v_fma_f32 v48, -v58, v59, 1.0
	v_exp_f32_e32 v51, v51
	v_fmac_f32_e32 v59, v48, v59
	v_div_scale_f32 v48, vcc, 1.0, v50, 1.0
	v_mul_f32_e32 v49, v48, v59
	v_fma_f32 v60, -v58, v49, v48
	v_fmac_f32_e32 v49, v60, v59
	v_add_f32_e32 v51, 1.0, v51
	v_fma_f32 v48, -v58, v49, v48
	v_div_scale_f32 v58, s[8:9], v51, v51, 1.0
	v_rcp_f32_e32 v60, v58
	v_div_fmas_f32 v48, v48, v59, v49
	v_div_fixup_f32 v59, v48, v50, 1.0
	v_fma_f32 v48, -v58, v60, 1.0
	v_fmac_f32_e32 v60, v48, v60
	v_div_scale_f32 v48, vcc, 1.0, v51, 1.0
	v_mul_f32_e32 v49, v48, v60
	v_fma_f32 v50, -v58, v49, v48
	v_fmac_f32_e32 v49, v50, v60
	v_fma_f32 v48, -v58, v49, v48
	v_div_fmas_f32 v48, v48, v60, v49
	v_div_fixup_f32 v51, v48, v51, 1.0
	v_cvt_pk_bf16_f32 v48, v52, v53
	v_lshl_add_u64 v[52:53], v[136:137], 1, s[30:31]
	v_cvt_pk_bf16_f32 v49, v54, v55
	v_cvt_pk_bf16_f32 v50, v56, v57
	v_cvt_pk_bf16_f32 v51, v59, v51
	global_store_dwordx4 v[52:53], v[48:51], off
	s_nop 1
	v_mov_b64_e32 v[48:49], v[216:217]
	v_mov_b64_e32 v[50:51], v[218:219]
	v_mov_b64_e32 v[52:53], v[220:221]
	v_mov_b64_e32 v[54:55], v[222:223]
	v_add_u32_e32 v56, 0x48000, v141
	v_add_u32_e32 v136, v56, v140
	v_pk_add_f32 v[44:45], v[44:45], v[48:49]
	s_nop 0
	v_mul_f32_e32 v44, 0xbfb8aa3b, v44
	v_exp_f32_e32 v44, v44
	v_mul_f32_e32 v45, 0xbfb8aa3b, v45
	v_pk_add_f32 v[46:47], v[46:47], v[50:51]
	v_exp_f32_e32 v45, v45
	v_add_f32_e32 v44, 1.0, v44
	v_div_scale_f32 v48, s[8:9], v44, v44, 1.0
	v_rcp_f32_e32 v49, v48
	v_add_f32_e32 v45, 1.0, v45
	v_mul_f32_e32 v46, 0xbfb8aa3b, v46
	v_exp_f32_e32 v46, v46
	v_fma_f32 v50, -v48, v49, 1.0
	v_fmac_f32_e32 v49, v50, v49
	v_div_scale_f32 v50, vcc, 1.0, v44, 1.0
	v_mul_f32_e32 v51, v50, v49
	v_fma_f32 v57, -v48, v51, v50
	v_fmac_f32_e32 v51, v57, v49
	v_fma_f32 v48, -v48, v51, v50
	v_div_scale_f32 v50, s[8:9], v45, v45, 1.0
	v_rcp_f32_e32 v57, v50
	v_div_fmas_f32 v48, v48, v49, v51
	v_div_fixup_f32 v44, v48, v44, 1.0
	v_add_f32_e32 v46, 1.0, v46
	v_fma_f32 v48, -v50, v57, 1.0
	v_fmac_f32_e32 v57, v48, v57
	v_div_scale_f32 v48, vcc, 1.0, v45, 1.0
	v_mul_f32_e32 v49, v48, v57
	v_fma_f32 v51, -v50, v49, v48
	v_fmac_f32_e32 v49, v51, v57
	v_fma_f32 v48, -v50, v49, v48
	v_div_scale_f32 v50, s[8:9], v46, v46, 1.0
	v_rcp_f32_e32 v51, v50
	v_div_fmas_f32 v48, v48, v57, v49
	v_mul_f32_e32 v47, 0xbfb8aa3b, v47
	v_div_fixup_f32 v45, v48, v45, 1.0
	v_fma_f32 v48, -v50, v51, 1.0
	v_exp_f32_e32 v47, v47
	v_fmac_f32_e32 v51, v48, v51
	v_div_scale_f32 v48, vcc, 1.0, v46, 1.0
	v_mul_f32_e32 v49, v48, v51
	v_fma_f32 v57, -v50, v49, v48
	v_fmac_f32_e32 v49, v57, v51
	v_add_f32_e32 v47, 1.0, v47
	v_fma_f32 v48, -v50, v49, v48
	v_div_scale_f32 v50, s[8:9], v47, v47, 1.0
	v_rcp_f32_e32 v57, v50
	v_pk_add_f32 v[40:41], v[40:41], v[52:53]
	v_div_fmas_f32 v48, v48, v51, v49
	v_mul_f32_e32 v40, 0xbfb8aa3b, v40
	v_div_fixup_f32 v46, v48, v46, 1.0
	v_fma_f32 v48, -v50, v57, 1.0
	v_exp_f32_e32 v40, v40
	v_fmac_f32_e32 v57, v48, v57
	v_div_scale_f32 v48, vcc, 1.0, v47, 1.0
	v_mul_f32_e32 v49, v48, v57
	v_fma_f32 v51, -v50, v49, v48
	v_fmac_f32_e32 v49, v51, v57
	v_add_f32_e32 v40, 1.0, v40
	v_fma_f32 v48, -v50, v49, v48
	v_div_scale_f32 v50, s[8:9], v40, v40, 1.0
	v_rcp_f32_e32 v51, v50
	v_div_fmas_f32 v48, v48, v57, v49
	v_mul_f32_e32 v41, 0xbfb8aa3b, v41
	v_div_fixup_f32 v47, v48, v47, 1.0
	v_fma_f32 v48, -v50, v51, 1.0
	v_exp_f32_e32 v41, v41
	v_fmac_f32_e32 v51, v48, v51
	v_div_scale_f32 v48, vcc, 1.0, v40, 1.0
	v_mul_f32_e32 v49, v48, v51
	v_fma_f32 v52, -v50, v49, v48
	v_fmac_f32_e32 v49, v52, v51
	v_add_f32_e32 v41, 1.0, v41
	v_fma_f32 v48, -v50, v49, v48
	v_div_scale_f32 v50, s[8:9], v41, v41, 1.0
	v_rcp_f32_e32 v52, v50
	v_pk_add_f32 v[42:43], v[42:43], v[54:55]
	v_div_fmas_f32 v48, v48, v51, v49
	v_mul_f32_e32 v42, 0xbfb8aa3b, v42
	v_div_fixup_f32 v48, v48, v40, 1.0
	v_fma_f32 v40, -v50, v52, 1.0
	v_exp_f32_e32 v42, v42
	v_fmac_f32_e32 v52, v40, v52
	v_div_scale_f32 v40, vcc, 1.0, v41, 1.0
	v_mul_f32_e32 v49, v40, v52
	v_fma_f32 v51, -v50, v49, v40
	v_fmac_f32_e32 v49, v51, v52
	v_add_f32_e32 v42, 1.0, v42
	v_fma_f32 v40, -v50, v49, v40
	v_div_scale_f32 v50, s[8:9], v42, v42, 1.0
	v_rcp_f32_e32 v51, v50
	v_div_fmas_f32 v40, v40, v52, v49
	v_mul_f32_e32 v43, 0xbfb8aa3b, v43
	v_div_fixup_f32 v49, v40, v41, 1.0
	v_fma_f32 v40, -v50, v51, 1.0
	v_exp_f32_e32 v43, v43
	v_fmac_f32_e32 v51, v40, v51
	v_div_scale_f32 v40, vcc, 1.0, v42, 1.0
	v_mul_f32_e32 v41, v40, v51
	v_fma_f32 v52, -v50, v41, v40
	v_fmac_f32_e32 v41, v52, v51
	v_add_f32_e32 v43, 1.0, v43
	v_fma_f32 v40, -v50, v41, v40
	v_div_scale_f32 v50, s[8:9], v43, v43, 1.0
	v_rcp_f32_e32 v52, v50
	v_div_fmas_f32 v40, v40, v51, v41
	v_div_fixup_f32 v51, v40, v42, 1.0
	v_fma_f32 v40, -v50, v52, 1.0
	v_fmac_f32_e32 v52, v40, v52
	v_div_scale_f32 v40, vcc, 1.0, v43, 1.0
	v_mul_f32_e32 v41, v40, v52
	v_fma_f32 v42, -v50, v41, v40
	v_fmac_f32_e32 v41, v42, v52
	v_fma_f32 v40, -v50, v41, v40
	v_div_fmas_f32 v40, v40, v52, v41
	v_div_fixup_f32 v43, v40, v43, 1.0
	v_cvt_pk_bf16_f32 v40, v44, v45
	v_lshl_add_u64 v[44:45], v[136:137], 1, s[30:31]
	v_cvt_pk_bf16_f32 v41, v46, v47
	v_cvt_pk_bf16_f32 v42, v48, v49
	v_cvt_pk_bf16_f32 v43, v51, v43
	global_store_dwordx4 v[44:45], v[40:43], off
	s_nop 1
	v_mov_b64_e32 v[40:41], v[224:225]
	v_mov_b64_e32 v[42:43], v[226:227]
	s_nop 0
	v_mov_b64_e32 v[44:45], v[228:229]
	v_mov_b64_e32 v[46:47], v[230:231]
	v_add_u32_e32 v136, v120, v56
	v_pk_add_f32 v[36:37], v[36:37], v[40:41]
	s_nop 0
	v_mul_f32_e32 v36, 0xbfb8aa3b, v36
	v_exp_f32_e32 v36, v36
	v_mul_f32_e32 v37, 0xbfb8aa3b, v37
	v_pk_add_f32 v[38:39], v[38:39], v[42:43]
	v_exp_f32_e32 v37, v37
	v_add_f32_e32 v36, 1.0, v36
	v_div_scale_f32 v40, s[8:9], v36, v36, 1.0
	v_rcp_f32_e32 v41, v40
	v_add_f32_e32 v37, 1.0, v37
	v_mul_f32_e32 v38, 0xbfb8aa3b, v38
	v_exp_f32_e32 v38, v38
	v_fma_f32 v42, -v40, v41, 1.0
	v_fmac_f32_e32 v41, v42, v41
	v_div_scale_f32 v42, vcc, 1.0, v36, 1.0
	v_mul_f32_e32 v43, v42, v41
	v_fma_f32 v48, -v40, v43, v42
	v_fmac_f32_e32 v43, v48, v41
	v_fma_f32 v40, -v40, v43, v42
	v_div_scale_f32 v42, s[8:9], v37, v37, 1.0
	v_rcp_f32_e32 v48, v42
	v_div_fmas_f32 v40, v40, v41, v43
	v_div_fixup_f32 v36, v40, v36, 1.0
	v_add_f32_e32 v38, 1.0, v38
	v_fma_f32 v40, -v42, v48, 1.0
	v_fmac_f32_e32 v48, v40, v48
	v_div_scale_f32 v40, vcc, 1.0, v37, 1.0
	v_mul_f32_e32 v41, v40, v48
	v_fma_f32 v43, -v42, v41, v40
	v_fmac_f32_e32 v41, v43, v48
	v_fma_f32 v40, -v42, v41, v40
	v_div_scale_f32 v42, s[8:9], v38, v38, 1.0
	v_rcp_f32_e32 v43, v42
	v_div_fmas_f32 v40, v40, v48, v41
	v_mul_f32_e32 v39, 0xbfb8aa3b, v39
	v_div_fixup_f32 v37, v40, v37, 1.0
	v_fma_f32 v40, -v42, v43, 1.0
	v_exp_f32_e32 v39, v39
	v_fmac_f32_e32 v43, v40, v43
	v_div_scale_f32 v40, vcc, 1.0, v38, 1.0
	v_mul_f32_e32 v41, v40, v43
	v_fma_f32 v48, -v42, v41, v40
	v_fmac_f32_e32 v41, v48, v43
	v_add_f32_e32 v39, 1.0, v39
	v_fma_f32 v40, -v42, v41, v40
	v_div_scale_f32 v42, s[8:9], v39, v39, 1.0
	v_rcp_f32_e32 v48, v42
	v_pk_add_f32 v[32:33], v[32:33], v[44:45]
	v_div_fmas_f32 v40, v40, v43, v41
	v_mul_f32_e32 v32, 0xbfb8aa3b, v32
	v_div_fixup_f32 v38, v40, v38, 1.0
	v_fma_f32 v40, -v42, v48, 1.0
	v_exp_f32_e32 v32, v32
	v_fmac_f32_e32 v48, v40, v48
	v_div_scale_f32 v40, vcc, 1.0, v39, 1.0
	v_mul_f32_e32 v41, v40, v48
	v_fma_f32 v43, -v42, v41, v40
	v_fmac_f32_e32 v41, v43, v48
	v_add_f32_e32 v32, 1.0, v32
	v_fma_f32 v40, -v42, v41, v40
	v_div_scale_f32 v42, s[8:9], v32, v32, 1.0
	v_rcp_f32_e32 v43, v42
	v_div_fmas_f32 v40, v40, v48, v41
	v_mul_f32_e32 v33, 0xbfb8aa3b, v33
	v_div_fixup_f32 v39, v40, v39, 1.0
	v_fma_f32 v40, -v42, v43, 1.0
	v_exp_f32_e32 v33, v33
	v_fmac_f32_e32 v43, v40, v43
	v_div_scale_f32 v40, vcc, 1.0, v32, 1.0
	v_mul_f32_e32 v41, v40, v43
	v_fma_f32 v44, -v42, v41, v40
	v_fmac_f32_e32 v41, v44, v43
	v_add_f32_e32 v33, 1.0, v33
	v_fma_f32 v40, -v42, v41, v40
	v_div_scale_f32 v42, s[8:9], v33, v33, 1.0
	v_rcp_f32_e32 v44, v42
	v_pk_add_f32 v[34:35], v[34:35], v[46:47]
	v_div_fmas_f32 v40, v40, v43, v41
	v_mul_f32_e32 v34, 0xbfb8aa3b, v34
	v_div_fixup_f32 v40, v40, v32, 1.0
	v_fma_f32 v32, -v42, v44, 1.0
	v_exp_f32_e32 v34, v34
	v_fmac_f32_e32 v44, v32, v44
	v_div_scale_f32 v32, vcc, 1.0, v33, 1.0
	v_mul_f32_e32 v41, v32, v44
	v_fma_f32 v43, -v42, v41, v32
	v_fmac_f32_e32 v41, v43, v44
	v_add_f32_e32 v34, 1.0, v34
	v_fma_f32 v32, -v42, v41, v32
	v_div_scale_f32 v42, s[8:9], v34, v34, 1.0
	v_rcp_f32_e32 v43, v42
	v_div_fmas_f32 v32, v32, v44, v41
	v_mul_f32_e32 v35, 0xbfb8aa3b, v35
	v_div_fixup_f32 v41, v32, v33, 1.0
	v_fma_f32 v32, -v42, v43, 1.0
	v_exp_f32_e32 v35, v35
	v_fmac_f32_e32 v43, v32, v43
	v_div_scale_f32 v32, vcc, 1.0, v34, 1.0
	v_mul_f32_e32 v33, v32, v43
	v_fma_f32 v44, -v42, v33, v32
	v_fmac_f32_e32 v33, v44, v43
	v_add_f32_e32 v35, 1.0, v35
	v_fma_f32 v32, -v42, v33, v32
	v_div_scale_f32 v42, s[8:9], v35, v35, 1.0
	v_rcp_f32_e32 v44, v42
	v_div_fmas_f32 v32, v32, v43, v33
	v_div_fixup_f32 v43, v32, v34, 1.0
	v_fma_f32 v32, -v42, v44, 1.0
	v_fmac_f32_e32 v44, v32, v44
	v_div_scale_f32 v32, vcc, 1.0, v35, 1.0
	v_mul_f32_e32 v33, v32, v44
	v_fma_f32 v34, -v42, v33, v32
	v_fmac_f32_e32 v33, v34, v44
	v_fma_f32 v32, -v42, v33, v32
	v_div_fmas_f32 v32, v32, v44, v33
	v_div_fixup_f32 v35, v32, v35, 1.0
	v_cvt_pk_bf16_f32 v32, v36, v37
	v_lshl_add_u64 v[36:37], v[136:137], 1, s[30:31]
	v_cvt_pk_bf16_f32 v33, v38, v39
	v_cvt_pk_bf16_f32 v34, v40, v41
	v_cvt_pk_bf16_f32 v35, v43, v35
	global_store_dwordx4 v[36:37], v[32:35], off
	s_nop 1
	v_mov_b64_e32 v[32:33], v[216:217]
	v_mov_b64_e32 v[34:35], v[218:219]
	v_mov_b64_e32 v[36:37], v[220:221]
	v_mov_b64_e32 v[38:39], v[222:223]
	v_add_u32_e32 v40, 0x50000, v141
	v_add_u32_e32 v136, v40, v140
	v_pk_add_f32 v[28:29], v[28:29], v[32:33]
	s_nop 0
	v_mul_f32_e32 v28, 0xbfb8aa3b, v28
	v_exp_f32_e32 v28, v28
	v_mul_f32_e32 v29, 0xbfb8aa3b, v29
	v_pk_add_f32 v[30:31], v[30:31], v[34:35]
	v_exp_f32_e32 v29, v29
	v_add_f32_e32 v28, 1.0, v28
	v_div_scale_f32 v32, s[8:9], v28, v28, 1.0
	v_rcp_f32_e32 v33, v32
	v_add_f32_e32 v29, 1.0, v29
	v_mul_f32_e32 v30, 0xbfb8aa3b, v30
	v_exp_f32_e32 v30, v30
	v_fma_f32 v34, -v32, v33, 1.0
	v_fmac_f32_e32 v33, v34, v33
	v_div_scale_f32 v34, vcc, 1.0, v28, 1.0
	v_mul_f32_e32 v35, v34, v33
	v_fma_f32 v41, -v32, v35, v34
	v_fmac_f32_e32 v35, v41, v33
	v_fma_f32 v32, -v32, v35, v34
	v_div_scale_f32 v34, s[8:9], v29, v29, 1.0
	v_rcp_f32_e32 v41, v34
	v_div_fmas_f32 v32, v32, v33, v35
	v_div_fixup_f32 v28, v32, v28, 1.0
	v_add_f32_e32 v30, 1.0, v30
	v_fma_f32 v32, -v34, v41, 1.0
	v_fmac_f32_e32 v41, v32, v41
	v_div_scale_f32 v32, vcc, 1.0, v29, 1.0
	v_mul_f32_e32 v33, v32, v41
	v_fma_f32 v35, -v34, v33, v32
	v_fmac_f32_e32 v33, v35, v41
	v_fma_f32 v32, -v34, v33, v32
	v_div_scale_f32 v34, s[8:9], v30, v30, 1.0
	v_rcp_f32_e32 v35, v34
	v_div_fmas_f32 v32, v32, v41, v33
	v_mul_f32_e32 v31, 0xbfb8aa3b, v31
	v_div_fixup_f32 v29, v32, v29, 1.0
	v_fma_f32 v32, -v34, v35, 1.0
	v_exp_f32_e32 v31, v31
	v_fmac_f32_e32 v35, v32, v35
	v_div_scale_f32 v32, vcc, 1.0, v30, 1.0
	v_mul_f32_e32 v33, v32, v35
	v_fma_f32 v41, -v34, v33, v32
	v_fmac_f32_e32 v33, v41, v35
	v_add_f32_e32 v31, 1.0, v31
	v_fma_f32 v32, -v34, v33, v32
	v_div_scale_f32 v34, s[8:9], v31, v31, 1.0
	v_rcp_f32_e32 v41, v34
	v_pk_add_f32 v[24:25], v[24:25], v[36:37]
	v_div_fmas_f32 v32, v32, v35, v33
	v_mul_f32_e32 v24, 0xbfb8aa3b, v24
	v_div_fixup_f32 v30, v32, v30, 1.0
	v_fma_f32 v32, -v34, v41, 1.0
	v_exp_f32_e32 v24, v24
	v_fmac_f32_e32 v41, v32, v41
	v_div_scale_f32 v32, vcc, 1.0, v31, 1.0
	v_mul_f32_e32 v33, v32, v41
	v_fma_f32 v35, -v34, v33, v32
	v_fmac_f32_e32 v33, v35, v41
	v_add_f32_e32 v24, 1.0, v24
	v_fma_f32 v32, -v34, v33, v32
	v_div_scale_f32 v34, s[8:9], v24, v24, 1.0
	v_rcp_f32_e32 v35, v34
	v_div_fmas_f32 v32, v32, v41, v33
	v_mul_f32_e32 v25, 0xbfb8aa3b, v25
	v_div_fixup_f32 v31, v32, v31, 1.0
	v_fma_f32 v32, -v34, v35, 1.0
	v_exp_f32_e32 v25, v25
	v_fmac_f32_e32 v35, v32, v35
	v_div_scale_f32 v32, vcc, 1.0, v24, 1.0
	v_mul_f32_e32 v33, v32, v35
	v_fma_f32 v36, -v34, v33, v32
	v_fmac_f32_e32 v33, v36, v35
	v_add_f32_e32 v25, 1.0, v25
	v_fma_f32 v32, -v34, v33, v32
	v_div_scale_f32 v34, s[8:9], v25, v25, 1.0
	v_rcp_f32_e32 v36, v34
	v_pk_add_f32 v[26:27], v[26:27], v[38:39]
	v_div_fmas_f32 v32, v32, v35, v33
	v_mul_f32_e32 v26, 0xbfb8aa3b, v26
	v_div_fixup_f32 v32, v32, v24, 1.0
	v_fma_f32 v24, -v34, v36, 1.0
	v_exp_f32_e32 v26, v26
	v_fmac_f32_e32 v36, v24, v36
	v_div_scale_f32 v24, vcc, 1.0, v25, 1.0
	v_mul_f32_e32 v33, v24, v36
	v_fma_f32 v35, -v34, v33, v24
	v_fmac_f32_e32 v33, v35, v36
	v_add_f32_e32 v26, 1.0, v26
	v_fma_f32 v24, -v34, v33, v24
	v_div_scale_f32 v34, s[8:9], v26, v26, 1.0
	v_rcp_f32_e32 v35, v34
	v_div_fmas_f32 v24, v24, v36, v33
	v_mul_f32_e32 v27, 0xbfb8aa3b, v27
	v_div_fixup_f32 v33, v24, v25, 1.0
	v_fma_f32 v24, -v34, v35, 1.0
	v_exp_f32_e32 v27, v27
	v_fmac_f32_e32 v35, v24, v35
	v_div_scale_f32 v24, vcc, 1.0, v26, 1.0
	v_mul_f32_e32 v25, v24, v35
	v_fma_f32 v36, -v34, v25, v24
	v_fmac_f32_e32 v25, v36, v35
	v_add_f32_e32 v27, 1.0, v27
	v_fma_f32 v24, -v34, v25, v24
	v_div_scale_f32 v34, s[8:9], v27, v27, 1.0
	v_rcp_f32_e32 v36, v34
	v_div_fmas_f32 v24, v24, v35, v25
	v_div_fixup_f32 v35, v24, v26, 1.0
	v_fma_f32 v24, -v34, v36, 1.0
	v_fmac_f32_e32 v36, v24, v36
	v_div_scale_f32 v24, vcc, 1.0, v27, 1.0
	v_mul_f32_e32 v25, v24, v36
	v_fma_f32 v26, -v34, v25, v24
	v_fmac_f32_e32 v25, v26, v36
	v_fma_f32 v24, -v34, v25, v24
	v_div_fmas_f32 v24, v24, v36, v25
	v_div_fixup_f32 v27, v24, v27, 1.0
	v_cvt_pk_bf16_f32 v24, v28, v29
	v_lshl_add_u64 v[28:29], v[136:137], 1, s[30:31]
	v_cvt_pk_bf16_f32 v25, v30, v31
	v_cvt_pk_bf16_f32 v26, v32, v33
	v_cvt_pk_bf16_f32 v27, v35, v27
	global_store_dwordx4 v[28:29], v[24:27], off
	s_nop 1
	v_mov_b64_e32 v[24:25], v[224:225]
	v_mov_b64_e32 v[26:27], v[226:227]
	s_nop 0
	v_mov_b64_e32 v[28:29], v[228:229]
	v_mov_b64_e32 v[30:31], v[230:231]
	v_add_u32_e32 v136, v120, v40
	v_pk_add_f32 v[20:21], v[20:21], v[24:25]
	s_nop 0
	v_mul_f32_e32 v20, 0xbfb8aa3b, v20
	v_exp_f32_e32 v20, v20
	v_mul_f32_e32 v21, 0xbfb8aa3b, v21
	v_pk_add_f32 v[22:23], v[22:23], v[26:27]
	v_exp_f32_e32 v21, v21
	v_add_f32_e32 v20, 1.0, v20
	v_div_scale_f32 v24, s[8:9], v20, v20, 1.0
	v_rcp_f32_e32 v25, v24
	v_add_f32_e32 v21, 1.0, v21
	v_mul_f32_e32 v22, 0xbfb8aa3b, v22
	v_exp_f32_e32 v22, v22
	v_fma_f32 v26, -v24, v25, 1.0
	v_fmac_f32_e32 v25, v26, v25
	v_div_scale_f32 v26, vcc, 1.0, v20, 1.0
	v_mul_f32_e32 v27, v26, v25
	v_fma_f32 v32, -v24, v27, v26
	v_fmac_f32_e32 v27, v32, v25
	v_fma_f32 v24, -v24, v27, v26
	v_div_scale_f32 v26, s[8:9], v21, v21, 1.0
	v_rcp_f32_e32 v32, v26
	v_div_fmas_f32 v24, v24, v25, v27
	v_div_fixup_f32 v20, v24, v20, 1.0
	v_add_f32_e32 v22, 1.0, v22
	v_fma_f32 v24, -v26, v32, 1.0
	v_fmac_f32_e32 v32, v24, v32
	v_div_scale_f32 v24, vcc, 1.0, v21, 1.0
	v_mul_f32_e32 v25, v24, v32
	v_fma_f32 v27, -v26, v25, v24
	v_fmac_f32_e32 v25, v27, v32
	v_fma_f32 v24, -v26, v25, v24
	v_div_scale_f32 v26, s[8:9], v22, v22, 1.0
	v_rcp_f32_e32 v27, v26
	v_div_fmas_f32 v24, v24, v32, v25
	v_mul_f32_e32 v23, 0xbfb8aa3b, v23
	v_div_fixup_f32 v21, v24, v21, 1.0
	v_fma_f32 v24, -v26, v27, 1.0
	v_exp_f32_e32 v23, v23
	v_fmac_f32_e32 v27, v24, v27
	v_div_scale_f32 v24, vcc, 1.0, v22, 1.0
	v_mul_f32_e32 v25, v24, v27
	v_fma_f32 v32, -v26, v25, v24
	v_fmac_f32_e32 v25, v32, v27
	v_add_f32_e32 v23, 1.0, v23
	v_fma_f32 v24, -v26, v25, v24
	v_div_scale_f32 v26, s[8:9], v23, v23, 1.0
	v_rcp_f32_e32 v32, v26
	v_pk_add_f32 v[16:17], v[16:17], v[28:29]
	v_div_fmas_f32 v24, v24, v27, v25
	v_mul_f32_e32 v16, 0xbfb8aa3b, v16
	v_div_fixup_f32 v22, v24, v22, 1.0
	v_fma_f32 v24, -v26, v32, 1.0
	v_exp_f32_e32 v16, v16
	v_fmac_f32_e32 v32, v24, v32
	v_div_scale_f32 v24, vcc, 1.0, v23, 1.0
	v_mul_f32_e32 v25, v24, v32
	v_fma_f32 v27, -v26, v25, v24
	v_fmac_f32_e32 v25, v27, v32
	v_add_f32_e32 v16, 1.0, v16
	v_fma_f32 v24, -v26, v25, v24
	v_div_scale_f32 v26, s[8:9], v16, v16, 1.0
	v_rcp_f32_e32 v27, v26
	v_div_fmas_f32 v24, v24, v32, v25
	v_mul_f32_e32 v17, 0xbfb8aa3b, v17
	v_div_fixup_f32 v23, v24, v23, 1.0
	v_fma_f32 v24, -v26, v27, 1.0
	v_exp_f32_e32 v17, v17
	v_fmac_f32_e32 v27, v24, v27
	v_div_scale_f32 v24, vcc, 1.0, v16, 1.0
	v_mul_f32_e32 v25, v24, v27
	v_fma_f32 v28, -v26, v25, v24
	v_fmac_f32_e32 v25, v28, v27
	v_add_f32_e32 v17, 1.0, v17
	v_fma_f32 v24, -v26, v25, v24
	v_div_scale_f32 v26, s[8:9], v17, v17, 1.0
	v_rcp_f32_e32 v28, v26
	v_pk_add_f32 v[18:19], v[18:19], v[30:31]
	v_div_fmas_f32 v24, v24, v27, v25
	v_mul_f32_e32 v18, 0xbfb8aa3b, v18
	v_div_fixup_f32 v24, v24, v16, 1.0
	v_fma_f32 v16, -v26, v28, 1.0
	v_exp_f32_e32 v18, v18
	v_fmac_f32_e32 v28, v16, v28
	v_div_scale_f32 v16, vcc, 1.0, v17, 1.0
	v_mul_f32_e32 v25, v16, v28
	v_fma_f32 v27, -v26, v25, v16
	v_fmac_f32_e32 v25, v27, v28
	v_add_f32_e32 v18, 1.0, v18
	v_fma_f32 v16, -v26, v25, v16
	v_div_scale_f32 v26, s[8:9], v18, v18, 1.0
	v_rcp_f32_e32 v27, v26
	v_div_fmas_f32 v16, v16, v28, v25
	v_mul_f32_e32 v19, 0xbfb8aa3b, v19
	v_div_fixup_f32 v25, v16, v17, 1.0
	v_fma_f32 v16, -v26, v27, 1.0
	v_exp_f32_e32 v19, v19
	v_fmac_f32_e32 v27, v16, v27
	v_div_scale_f32 v16, vcc, 1.0, v18, 1.0
	v_mul_f32_e32 v17, v16, v27
	v_fma_f32 v28, -v26, v17, v16
	v_fmac_f32_e32 v17, v28, v27
	v_add_f32_e32 v19, 1.0, v19
	v_fma_f32 v16, -v26, v17, v16
	v_div_scale_f32 v26, s[8:9], v19, v19, 1.0
	v_rcp_f32_e32 v28, v26
	v_div_fmas_f32 v16, v16, v27, v17
	v_div_fixup_f32 v27, v16, v18, 1.0
	v_fma_f32 v16, -v26, v28, 1.0
	v_fmac_f32_e32 v28, v16, v28
	v_div_scale_f32 v16, vcc, 1.0, v19, 1.0
	v_mul_f32_e32 v17, v16, v28
	v_fma_f32 v18, -v26, v17, v16
	v_fmac_f32_e32 v17, v18, v28
	v_fma_f32 v16, -v26, v17, v16
	v_div_fmas_f32 v16, v16, v28, v17
	v_div_fixup_f32 v19, v16, v19, 1.0
	v_cvt_pk_bf16_f32 v16, v20, v21
	v_lshl_add_u64 v[20:21], v[136:137], 1, s[30:31]
	v_cvt_pk_bf16_f32 v17, v22, v23
	v_cvt_pk_bf16_f32 v18, v24, v25
	v_cvt_pk_bf16_f32 v19, v27, v19
	global_store_dwordx4 v[20:21], v[16:19], off
	s_nop 1
	v_mov_b64_e32 v[16:17], v[216:217]
	v_mov_b64_e32 v[18:19], v[218:219]
	v_mov_b64_e32 v[20:21], v[220:221]
	v_mov_b64_e32 v[22:23], v[222:223]
	v_add_u32_e32 v24, 0x58000, v141
	v_add_u32_e32 v136, v24, v140
	v_pk_add_f32 v[12:13], v[12:13], v[16:17]
	s_nop 0
	v_mul_f32_e32 v12, 0xbfb8aa3b, v12
	v_exp_f32_e32 v12, v12
	v_mul_f32_e32 v13, 0xbfb8aa3b, v13
	v_pk_add_f32 v[14:15], v[14:15], v[18:19]
	v_exp_f32_e32 v13, v13
	v_add_f32_e32 v12, 1.0, v12
	v_div_scale_f32 v16, s[8:9], v12, v12, 1.0
	v_rcp_f32_e32 v17, v16
	v_add_f32_e32 v13, 1.0, v13
	v_mul_f32_e32 v14, 0xbfb8aa3b, v14
	v_exp_f32_e32 v14, v14
	v_fma_f32 v18, -v16, v17, 1.0
	v_fmac_f32_e32 v17, v18, v17
	v_div_scale_f32 v18, vcc, 1.0, v12, 1.0
	v_mul_f32_e32 v19, v18, v17
	v_fma_f32 v25, -v16, v19, v18
	v_fmac_f32_e32 v19, v25, v17
	v_fma_f32 v16, -v16, v19, v18
	v_div_scale_f32 v18, s[8:9], v13, v13, 1.0
	v_rcp_f32_e32 v25, v18
	v_div_fmas_f32 v16, v16, v17, v19
	v_div_fixup_f32 v12, v16, v12, 1.0
	v_add_f32_e32 v14, 1.0, v14
	v_fma_f32 v16, -v18, v25, 1.0
	v_fmac_f32_e32 v25, v16, v25
	v_div_scale_f32 v16, vcc, 1.0, v13, 1.0
	v_mul_f32_e32 v17, v16, v25
	v_fma_f32 v19, -v18, v17, v16
	v_fmac_f32_e32 v17, v19, v25
	v_fma_f32 v16, -v18, v17, v16
	v_div_scale_f32 v18, s[8:9], v14, v14, 1.0
	v_rcp_f32_e32 v19, v18
	v_div_fmas_f32 v16, v16, v25, v17
	v_mul_f32_e32 v15, 0xbfb8aa3b, v15
	v_div_fixup_f32 v13, v16, v13, 1.0
	v_fma_f32 v16, -v18, v19, 1.0
	v_exp_f32_e32 v15, v15
	v_fmac_f32_e32 v19, v16, v19
	v_div_scale_f32 v16, vcc, 1.0, v14, 1.0
	v_mul_f32_e32 v17, v16, v19
	v_fma_f32 v25, -v18, v17, v16
	v_fmac_f32_e32 v17, v25, v19
	v_add_f32_e32 v15, 1.0, v15
	v_fma_f32 v16, -v18, v17, v16
	v_div_scale_f32 v18, s[8:9], v15, v15, 1.0
	v_rcp_f32_e32 v25, v18
	v_pk_add_f32 v[8:9], v[8:9], v[20:21]
	v_div_fmas_f32 v16, v16, v19, v17
	v_mul_f32_e32 v8, 0xbfb8aa3b, v8
	v_div_fixup_f32 v14, v16, v14, 1.0
	v_fma_f32 v16, -v18, v25, 1.0
	v_exp_f32_e32 v8, v8
	v_fmac_f32_e32 v25, v16, v25
	v_div_scale_f32 v16, vcc, 1.0, v15, 1.0
	v_mul_f32_e32 v17, v16, v25
	v_fma_f32 v19, -v18, v17, v16
	v_fmac_f32_e32 v17, v19, v25
	v_add_f32_e32 v8, 1.0, v8
	v_fma_f32 v16, -v18, v17, v16
	v_div_scale_f32 v18, s[8:9], v8, v8, 1.0
	v_rcp_f32_e32 v19, v18
	v_div_fmas_f32 v16, v16, v25, v17
	v_mul_f32_e32 v9, 0xbfb8aa3b, v9
	v_div_fixup_f32 v15, v16, v15, 1.0
	v_fma_f32 v16, -v18, v19, 1.0
	v_exp_f32_e32 v9, v9
	v_fmac_f32_e32 v19, v16, v19
	v_div_scale_f32 v16, vcc, 1.0, v8, 1.0
	v_mul_f32_e32 v17, v16, v19
	v_fma_f32 v20, -v18, v17, v16
	v_fmac_f32_e32 v17, v20, v19
	v_add_f32_e32 v9, 1.0, v9
	v_fma_f32 v16, -v18, v17, v16
	v_div_scale_f32 v18, s[8:9], v9, v9, 1.0
	v_rcp_f32_e32 v20, v18
	v_pk_add_f32 v[10:11], v[10:11], v[22:23]
	v_div_fmas_f32 v16, v16, v19, v17
	v_mul_f32_e32 v10, 0xbfb8aa3b, v10
	v_div_fixup_f32 v16, v16, v8, 1.0
	v_fma_f32 v8, -v18, v20, 1.0
	v_exp_f32_e32 v10, v10
	v_fmac_f32_e32 v20, v8, v20
	v_div_scale_f32 v8, vcc, 1.0, v9, 1.0
	v_mul_f32_e32 v17, v8, v20
	v_fma_f32 v19, -v18, v17, v8
	v_fmac_f32_e32 v17, v19, v20
	v_add_f32_e32 v10, 1.0, v10
	v_fma_f32 v8, -v18, v17, v8
	v_div_scale_f32 v18, s[8:9], v10, v10, 1.0
	v_rcp_f32_e32 v19, v18
	v_div_fmas_f32 v8, v8, v20, v17
	v_mul_f32_e32 v11, 0xbfb8aa3b, v11
	v_div_fixup_f32 v17, v8, v9, 1.0
	v_fma_f32 v8, -v18, v19, 1.0
	v_exp_f32_e32 v11, v11
	v_fmac_f32_e32 v19, v8, v19
	v_div_scale_f32 v8, vcc, 1.0, v10, 1.0
	v_mul_f32_e32 v9, v8, v19
	v_fma_f32 v20, -v18, v9, v8
	v_fmac_f32_e32 v9, v20, v19
	v_add_f32_e32 v11, 1.0, v11
	v_fma_f32 v8, -v18, v9, v8
	v_div_scale_f32 v18, s[8:9], v11, v11, 1.0
	v_rcp_f32_e32 v20, v18
	v_div_fmas_f32 v8, v8, v19, v9
	v_div_fixup_f32 v19, v8, v10, 1.0
	v_fma_f32 v8, -v18, v20, 1.0
	v_fmac_f32_e32 v20, v8, v20
	v_div_scale_f32 v8, vcc, 1.0, v11, 1.0
	v_mul_f32_e32 v9, v8, v20
	v_fma_f32 v10, -v18, v9, v8
	v_fmac_f32_e32 v9, v10, v20
	v_fma_f32 v8, -v18, v9, v8
	v_div_fmas_f32 v8, v8, v20, v9
	v_div_fixup_f32 v11, v8, v11, 1.0
	v_cvt_pk_bf16_f32 v8, v12, v13
	v_lshl_add_u64 v[12:13], v[136:137], 1, s[30:31]
	v_cvt_pk_bf16_f32 v9, v14, v15
	v_cvt_pk_bf16_f32 v10, v16, v17
	v_cvt_pk_bf16_f32 v11, v19, v11
	global_store_dwordx4 v[12:13], v[8:11], off
	s_nop 1
	v_mov_b64_e32 v[8:9], v[224:225]
	v_mov_b64_e32 v[10:11], v[226:227]
	s_nop 0
	v_mov_b64_e32 v[12:13], v[228:229]
	v_mov_b64_e32 v[14:15], v[230:231]
	v_add_u32_e32 v136, v120, v24
	v_pk_add_f32 v[4:5], v[4:5], v[8:9]
	s_nop 0
	v_mul_f32_e32 v4, 0xbfb8aa3b, v4
	v_exp_f32_e32 v4, v4
	v_mul_f32_e32 v5, 0xbfb8aa3b, v5
	v_pk_add_f32 v[6:7], v[6:7], v[10:11]
	v_exp_f32_e32 v5, v5
	v_add_f32_e32 v4, 1.0, v4
	v_div_scale_f32 v8, s[8:9], v4, v4, 1.0
	v_rcp_f32_e32 v9, v8
	v_add_f32_e32 v5, 1.0, v5
	v_mul_f32_e32 v6, 0xbfb8aa3b, v6
	v_exp_f32_e32 v6, v6
	v_fma_f32 v10, -v8, v9, 1.0
	v_fmac_f32_e32 v9, v10, v9
	v_div_scale_f32 v10, vcc, 1.0, v4, 1.0
	v_mul_f32_e32 v11, v10, v9
	v_fma_f32 v16, -v8, v11, v10
	v_fmac_f32_e32 v11, v16, v9
	v_fma_f32 v8, -v8, v11, v10
	v_div_scale_f32 v10, s[8:9], v5, v5, 1.0
	v_rcp_f32_e32 v16, v10
	v_div_fmas_f32 v8, v8, v9, v11
	v_div_fixup_f32 v4, v8, v4, 1.0
	v_add_f32_e32 v6, 1.0, v6
	v_fma_f32 v8, -v10, v16, 1.0
	v_fmac_f32_e32 v16, v8, v16
	v_div_scale_f32 v8, vcc, 1.0, v5, 1.0
	v_mul_f32_e32 v9, v8, v16
	v_fma_f32 v11, -v10, v9, v8
	v_fmac_f32_e32 v9, v11, v16
	v_fma_f32 v8, -v10, v9, v8
	v_div_scale_f32 v10, s[8:9], v6, v6, 1.0
	v_rcp_f32_e32 v11, v10
	v_div_fmas_f32 v8, v8, v16, v9
	v_mul_f32_e32 v7, 0xbfb8aa3b, v7
	v_div_fixup_f32 v5, v8, v5, 1.0
	v_fma_f32 v8, -v10, v11, 1.0
	v_exp_f32_e32 v7, v7
	v_fmac_f32_e32 v11, v8, v11
	v_div_scale_f32 v8, vcc, 1.0, v6, 1.0
	v_mul_f32_e32 v9, v8, v11
	v_fma_f32 v16, -v10, v9, v8
	v_fmac_f32_e32 v9, v16, v11
	v_add_f32_e32 v7, 1.0, v7
	v_fma_f32 v8, -v10, v9, v8
	v_div_scale_f32 v10, s[8:9], v7, v7, 1.0
	v_rcp_f32_e32 v16, v10
	v_pk_add_f32 v[0:1], v[0:1], v[12:13]
	v_div_fmas_f32 v8, v8, v11, v9
	v_mul_f32_e32 v0, 0xbfb8aa3b, v0
	v_div_fixup_f32 v6, v8, v6, 1.0
	v_fma_f32 v8, -v10, v16, 1.0
	v_exp_f32_e32 v0, v0
	v_fmac_f32_e32 v16, v8, v16
	v_div_scale_f32 v8, vcc, 1.0, v7, 1.0
	v_mul_f32_e32 v9, v8, v16
	v_fma_f32 v11, -v10, v9, v8
	v_fmac_f32_e32 v9, v11, v16
	v_add_f32_e32 v0, 1.0, v0
	v_fma_f32 v8, -v10, v9, v8
	v_div_scale_f32 v10, s[8:9], v0, v0, 1.0
	v_rcp_f32_e32 v11, v10
	v_div_fmas_f32 v8, v8, v16, v9
	v_mul_f32_e32 v1, 0xbfb8aa3b, v1
	v_div_fixup_f32 v7, v8, v7, 1.0
	v_fma_f32 v8, -v10, v11, 1.0
	v_exp_f32_e32 v1, v1
	v_fmac_f32_e32 v11, v8, v11
	v_div_scale_f32 v8, vcc, 1.0, v0, 1.0
	v_mul_f32_e32 v9, v8, v11
	v_fma_f32 v12, -v10, v9, v8
	v_fmac_f32_e32 v9, v12, v11
	v_add_f32_e32 v1, 1.0, v1
	v_fma_f32 v8, -v10, v9, v8
	v_div_scale_f32 v10, s[8:9], v1, v1, 1.0
	v_rcp_f32_e32 v12, v10
	v_pk_add_f32 v[2:3], v[2:3], v[14:15]
	v_div_fmas_f32 v8, v8, v11, v9
	v_mul_f32_e32 v2, 0xbfb8aa3b, v2
	v_div_fixup_f32 v8, v8, v0, 1.0
	v_fma_f32 v0, -v10, v12, 1.0
	v_exp_f32_e32 v2, v2
	v_fmac_f32_e32 v12, v0, v12
	v_div_scale_f32 v0, vcc, 1.0, v1, 1.0
	v_mul_f32_e32 v9, v0, v12
	v_fma_f32 v11, -v10, v9, v0
	v_fmac_f32_e32 v9, v11, v12
	v_add_f32_e32 v2, 1.0, v2
	v_fma_f32 v0, -v10, v9, v0
	v_div_scale_f32 v10, s[8:9], v2, v2, 1.0
	v_rcp_f32_e32 v11, v10
	v_div_fmas_f32 v0, v0, v12, v9
	v_mul_f32_e32 v3, 0xbfb8aa3b, v3
	v_div_fixup_f32 v9, v0, v1, 1.0
	v_fma_f32 v0, -v10, v11, 1.0
	v_exp_f32_e32 v3, v3
	v_fmac_f32_e32 v11, v0, v11
	v_div_scale_f32 v0, vcc, 1.0, v2, 1.0
	v_mul_f32_e32 v1, v0, v11
	v_fma_f32 v12, -v10, v1, v0
	v_fmac_f32_e32 v1, v12, v11
	v_add_f32_e32 v3, 1.0, v3
	v_fma_f32 v0, -v10, v1, v0
	v_div_scale_f32 v10, s[8:9], v3, v3, 1.0
	v_rcp_f32_e32 v12, v10
	v_div_fmas_f32 v0, v0, v11, v1
	v_div_fixup_f32 v11, v0, v2, 1.0
	s_mov_b64 s[8:9], -1
	v_fma_f32 v0, -v10, v12, 1.0
	v_fmac_f32_e32 v12, v0, v12
	v_div_scale_f32 v0, vcc, 1.0, v3, 1.0
	v_mul_f32_e32 v1, v0, v12
	v_fma_f32 v2, -v10, v1, v0
	v_fmac_f32_e32 v1, v2, v12
	v_fma_f32 v0, -v10, v1, v0
	v_div_fmas_f32 v0, v0, v12, v1
	v_div_fixup_f32 v3, v0, v3, 1.0
	v_cvt_pk_bf16_f32 v0, v4, v5
	v_lshl_add_u64 v[4:5], v[136:137], 1, s[30:31]
	v_cvt_pk_bf16_f32 v1, v6, v7
	v_cvt_pk_bf16_f32 v2, v8, v9
	v_cvt_pk_bf16_f32 v3, v11, v3
	global_store_dwordx4 v[4:5], v[0:3], off
	s_andn2_b64 vcc, exec, s[24:25]
	s_cbranch_vccnz .LBB0_408
	s_andn2_b64 vcc, exec, s[4:5]
	s_cbranch_vccnz .LBB0_407
	s_barrier
	s_branch .LBB0_407
